# v54 plus rss-load hoist in the P3 sample in-projection epilogues
# baseline (speedup 1.0000x reference)
; __device__ __forceinline__ unsigned cvt_pk_bf16(float lo, float hi) { unsigned r; asm volatile("v_cvt_pk_bf16_f32 %0, %1, %2" : "=v"(r) : "v"(lo), "v"(hi)); return r; }
; __device__ __forceinline__ float sigmoid_f(float x) { return __builtin_amdgcn_rcpf(1.f + __builtin_amdgcn_exp2f(-1.4426950408889634f * x)); }
;     __device__ __forceinline__ void operator()(const f32x4 (&acc)[2][2][4][2], const Unit& u, int wr, int wc, int fr, int fq) const {
;     ...
;             const int col0 = (pn - 13) * 256 + wc * 32 + 8 * fq;
;             f32x4 bv[2][2];
; #pragma unroll
;             for (int bj = 0; bj < 2; ++bj)
; #pragma unroll
;                 for (int n = 0; n < 2; ++n) bv[bj][n] = *(const f32x4*)(b_gate + col0 + bj * HALF + 4 * n);
; #pragma unroll
;             for (int ai = 0; ai < 2; ++ai)
; #pragma unroll
;                 for (int m = 0; m < 4; ++m) {
;                     const int row = row0 + ai * HALF + m * 16; const float r = __builtin_amdgcn_rsqf(rss[row] * (1.f / 1024.f) + NEPS);
; #pragma unroll
;                     for (int bj = 0; bj < 2; ++bj) {
;                         float o[8];
; #pragma unroll
;                         for (int n = 0; n < 2; ++n)
; #pragma unroll
;                             for (int e = 0; e < 4; ++e) o[4 * n + e] = sigmoid_f(acc[ai][bj][m][n][e] * r + bv[bj][n][e]);
;                         u32x4 w; w.x = cvt_pk_bf16(o[0], o[1]); w.y = cvt_pk_bf16(o[2], o[3]); w.z = cvt_pk_bf16(o[4], o[5]); w.w = cvt_pk_bf16(o[6], o[7]);
;                         *(u32x4*)(G + (size_t)row * 2048 + col0 + bj * HALF) = w;
;                     }
;                 }
.LBB0_750:
	s_lshl_b32 s27, s0, 8
	s_add_i32 s27, s27, s67
	s_cmp_gt_i32 s0, 63
	s_cselect_b64 s[52:53], -1, 0
	s_cmp_lt_i32 s0, 64
	v_or_b32_e32 v180, s27, v163
	s_cselect_b64 s[50:51], -1, 0
	s_cmp_gt_i32 s38, 3
	s_mov_b64 s[2:3], -1
	s_cbranch_scc0 .LBB0_916
	s_cmp_gt_u32 s38, 12
	s_cbranch_scc0 .LBB0_753
	v_ashrrev_i32_e32 v181, 31, v180
	v_lshl_add_u64 v[146:147], v[180:181], 2, s[40:41]
	global_load_dword v236, v[146:147], off
	global_load_dword v237, v[146:147], off offset:64
	global_load_dword v238, v[146:147], off offset:128
	global_load_dword v239, v[146:147], off offset:192
	global_load_dword v240, v[146:147], off offset:512
	global_load_dword v241, v[146:147], off offset:576
	global_load_dword v242, v[146:147], off offset:640
	global_load_dword v243, v[146:147], off offset:704
	v_readlane_b32 s2, v250, 14
	v_lshl_add_u32 v168, s38, 8, v202
	v_readlane_b32 s3, v250, 15
	v_lshlrev_b64 v[148:149], 12, v[180:181]
	v_lshl_add_u64 v[148:149], s[94:95], 0, v[148:149]
	v_lshl_add_u64 v[130:131], v[168:169], 2, s[2:3]
	global_load_dwordx4 v[142:145], v[130:131], off
	global_load_dwordx4 v[138:141], v[130:131], off offset:16
	global_load_dwordx4 v[134:137], v[130:131], off offset:512
	s_nop 0
	global_load_dwordx4 v[130:133], v[130:131], off offset:528
	s_mov_b32 s0, 0x80000
	s_mov_b64 s[2:3], 0x80000
	s_waitcnt vmcnt(0)
	v_mov_b32_e32 v150, v236
	v_fmamk_f32 v150, v150, 0x3a800000, v210
	v_rsq_f32_e32 v152, v150
	v_lshlrev_b64 v[150:151], 1, v[168:169]
	v_lshl_add_u64 v[148:149], v[148:149], 0, v[150:151]
	v_fma_f32 v153, v126, v152, v142
	v_fma_f32 v154, v127, v152, v143
	v_fma_f32 v155, v128, v152, v144
	v_fma_f32 v156, v129, v152, v145
	v_fma_f32 v157, v122, v152, v138
	v_fma_f32 v158, v123, v152, v139
	v_fma_f32 v159, v124, v152, v140
	v_fma_f32 v160, v125, v152, v141
	v_fma_f32 v161, v118, v152, v134
	v_fma_f32 v168, v119, v152, v135
	v_fma_f32 v181, v120, v152, v136
	v_fma_f32 v182, v121, v152, v137
	v_fma_f32 v183, v114, v152, v130
	v_fma_f32 v184, v115, v152, v131
	v_fma_f32 v185, v116, v152, v132
	v_fma_f32 v152, v117, v152, v133
	v_mul_f32_e32 v153, 0xbfb8aa3b, v153
	v_mul_f32_e32 v154, 0xbfb8aa3b, v154
	v_mul_f32_e32 v155, 0xbfb8aa3b, v155
	v_mul_f32_e32 v152, 0xbfb8aa3b, v152
	v_mul_f32_e32 v156, 0xbfb8aa3b, v156
	v_mul_f32_e32 v157, 0xbfb8aa3b, v157
	v_mul_f32_e32 v158, 0xbfb8aa3b, v158
	v_mul_f32_e32 v159, 0xbfb8aa3b, v159
	v_mul_f32_e32 v160, 0xbfb8aa3b, v160
	v_mul_f32_e32 v161, 0xbfb8aa3b, v161
	v_mul_f32_e32 v168, 0xbfb8aa3b, v168
	v_exp_f32_e32 v153, v153
	v_exp_f32_e32 v154, v154
	v_exp_f32_e32 v155, v155
	v_exp_f32_e32 v152, v152
	v_mul_f32_e32 v181, 0xbfb8aa3b, v181
	v_mul_f32_e32 v182, 0xbfb8aa3b, v182
	v_mul_f32_e32 v183, 0xbfb8aa3b, v183
	v_mul_f32_e32 v184, 0xbfb8aa3b, v184
	v_mul_f32_e32 v185, 0xbfb8aa3b, v185
	v_exp_f32_e32 v156, v156
	v_exp_f32_e32 v157, v157
	v_exp_f32_e32 v158, v158
	v_exp_f32_e32 v159, v159
	v_exp_f32_e32 v160, v160
	v_exp_f32_e32 v161, v161
	v_exp_f32_e32 v168, v168
	v_exp_f32_e32 v181, v181
	v_exp_f32_e32 v182, v182
	v_exp_f32_e32 v183, v183
	v_exp_f32_e32 v184, v184
	v_exp_f32_e32 v185, v185
	v_add_f32_e32 v153, 1.0, v153
	v_add_f32_e32 v154, 1.0, v154
	v_add_f32_e32 v155, 1.0, v155
	v_add_f32_e32 v152, 1.0, v152
	v_add_f32_e32 v156, 1.0, v156
	v_add_f32_e32 v157, 1.0, v157
	v_add_f32_e32 v158, 1.0, v158
	v_add_f32_e32 v159, 1.0, v159
	v_add_f32_e32 v160, 1.0, v160
	v_add_f32_e32 v161, 1.0, v161
	v_add_f32_e32 v168, 1.0, v168
	v_rcp_f32_e32 v153, v153
	v_rcp_f32_e32 v154, v154
	v_rcp_f32_e32 v155, v155
	v_rcp_f32_e32 v186, v152
	v_cvt_pk_bf16_f32 v152, v153, v154
	v_add_f32_e32 v181, 1.0, v181
	v_add_f32_e32 v182, 1.0, v182
	v_add_f32_e32 v183, 1.0, v183
	v_add_f32_e32 v184, 1.0, v184
	v_add_f32_e32 v185, 1.0, v185
	v_rcp_f32_e32 v156, v156
	v_rcp_f32_e32 v157, v157
	v_rcp_f32_e32 v158, v158
	v_rcp_f32_e32 v159, v159
	v_rcp_f32_e32 v160, v160
	v_rcp_f32_e32 v161, v161
	v_rcp_f32_e32 v168, v168
	v_cvt_pk_bf16_f32 v153, v155, v156
	v_cvt_pk_bf16_f32 v154, v157, v158
	v_cvt_pk_bf16_f32 v155, v159, v160
	global_store_dwordx4 v[148:149], v[152:155], off
	v_rcp_f32_e32 v181, v181
	v_rcp_f32_e32 v182, v182
	v_cvt_pk_bf16_f32 v152, v161, v168
	v_rcp_f32_e32 v183, v183
	v_rcp_f32_e32 v184, v184
	v_rcp_f32_e32 v185, v185
	v_cvt_pk_bf16_f32 v153, v181, v182
	v_cvt_pk_bf16_f32 v154, v183, v184
	v_cvt_pk_bf16_f32 v155, v185, v186
	global_store_dwordx4 v[148:149], v[152:155], off offset:256
	s_nop 1
	v_or_b32_e32 v152, 16, v180
	v_ashrrev_i32_e32 v153, 31, v152
	v_lshl_add_u64 v[154:155], v[152:153], 2, s[40:41]
	s_nop 0
	v_lshlrev_b64 v[152:153], 12, v[152:153]
	v_lshl_add_u64 v[152:153], s[94:95], 0, v[152:153]
	v_lshl_add_u64 v[156:157], v[152:153], 0, v[150:151]
	s_waitcnt vmcnt(7)
; __device__ __forceinline__ unsigned cvt_pk_bf16(float lo, float hi) { unsigned r; asm volatile("v_cvt_pk_bf16_f32 %0, %1, %2" : "=v"(r) : "v"(lo), "v"(hi)); return r; }
; __device__ __forceinline__ float sigmoid_f(float x) { return __builtin_amdgcn_rcpf(1.f + __builtin_amdgcn_exp2f(-1.4426950408889634f * x)); }
;     __device__ __forceinline__ void operator()(const f32x4 (&acc)[2][2][4][2], const Unit& u, int wr, int wc, int fr, int fq) const {
;     ...
;             for (int ai = 0; ai < 2; ++ai)
; #pragma unroll
;                 for (int m = 0; m < 4; ++m) {
;                     const int row = row0 + ai * HALF + m * 16; const float r = __builtin_amdgcn_rsqf(rss[row] * (1.f / 1024.f) + NEPS);
; #pragma unroll
;                     for (int bj = 0; bj < 2; ++bj) {
;                         float o[8];
; #pragma unroll
;                         for (int n = 0; n < 2; ++n)
; #pragma unroll
;                             for (int e = 0; e < 4; ++e) o[4 * n + e] = sigmoid_f(acc[ai][bj][m][n][e] * r + bv[bj][n][e]);
;                         u32x4 w; w.x = cvt_pk_bf16(o[0], o[1]); w.y = cvt_pk_bf16(o[2], o[3]); w.z = cvt_pk_bf16(o[4], o[5]); w.w = cvt_pk_bf16(o[6], o[7]);
;                         *(u32x4*)(G + (size_t)row * 2048 + col0 + bj * HALF) = w;
;                     }
	v_mov_b32_e32 v154, v237
	v_fmamk_f32 v154, v154, 0x3a800000, v210
	v_rsq_f32_e32 v154, v154
	s_nop 0
	v_fma_f32 v152, v110, v154, v142
	v_fma_f32 v153, v111, v154, v143
	v_fma_f32 v155, v112, v154, v144
	v_mul_f32_e32 v152, 0xbfb8aa3b, v152
	v_fma_f32 v158, v113, v154, v145
	v_fma_f32 v159, v106, v154, v138
	v_fma_f32 v160, v107, v154, v139
	v_fma_f32 v161, v108, v154, v140
	v_fma_f32 v168, v109, v154, v141
	v_fma_f32 v181, v102, v154, v134
	v_fma_f32 v182, v103, v154, v135
	v_fma_f32 v183, v104, v154, v136
	v_fma_f32 v184, v105, v154, v137
	v_fma_f32 v185, v98, v154, v130
	v_fma_f32 v186, v99, v154, v131
	v_fma_f32 v187, v100, v154, v132
	v_fma_f32 v154, v101, v154, v133
	v_mul_f32_e32 v153, 0xbfb8aa3b, v153
	v_mul_f32_e32 v155, 0xbfb8aa3b, v155
	v_exp_f32_e32 v152, v152
	v_mul_f32_e32 v158, 0xbfb8aa3b, v158
	v_mul_f32_e32 v159, 0xbfb8aa3b, v159
	v_mul_f32_e32 v160, 0xbfb8aa3b, v160
	v_mul_f32_e32 v161, 0xbfb8aa3b, v161
	v_mul_f32_e32 v168, 0xbfb8aa3b, v168
	v_mul_f32_e32 v181, 0xbfb8aa3b, v181
	v_mul_f32_e32 v182, 0xbfb8aa3b, v182
	v_mul_f32_e32 v154, 0xbfb8aa3b, v154
	v_exp_f32_e32 v153, v153
	v_exp_f32_e32 v155, v155
	v_mul_f32_e32 v183, 0xbfb8aa3b, v183
	v_mul_f32_e32 v184, 0xbfb8aa3b, v184
	v_mul_f32_e32 v185, 0xbfb8aa3b, v185
	v_mul_f32_e32 v186, 0xbfb8aa3b, v186
	v_mul_f32_e32 v187, 0xbfb8aa3b, v187
	v_exp_f32_e32 v158, v158
	v_exp_f32_e32 v159, v159
	v_exp_f32_e32 v160, v160
	v_exp_f32_e32 v161, v161
	v_exp_f32_e32 v168, v168
	v_exp_f32_e32 v181, v181
	v_exp_f32_e32 v182, v182
	v_exp_f32_e32 v154, v154
	v_exp_f32_e32 v183, v183
	v_exp_f32_e32 v184, v184
	v_exp_f32_e32 v185, v185
	v_exp_f32_e32 v186, v186
	v_exp_f32_e32 v187, v187
	v_add_f32_e32 v152, 1.0, v152
	v_add_f32_e32 v153, 1.0, v153
	v_add_f32_e32 v155, 1.0, v155
	v_rcp_f32_e32 v152, v152
	v_add_f32_e32 v158, 1.0, v158
	v_add_f32_e32 v159, 1.0, v159
	v_add_f32_e32 v160, 1.0, v160
	v_add_f32_e32 v161, 1.0, v161
	v_add_f32_e32 v168, 1.0, v168
	v_add_f32_e32 v181, 1.0, v181
	v_add_f32_e32 v182, 1.0, v182
	v_add_f32_e32 v154, 1.0, v154
	v_rcp_f32_e32 v153, v153
	v_rcp_f32_e32 v155, v155
	v_cvt_pk_bf16_f32 v152, v152, v153
	v_add_f32_e32 v183, 1.0, v183
	v_add_f32_e32 v184, 1.0, v184
	v_add_f32_e32 v185, 1.0, v185
	v_add_f32_e32 v186, 1.0, v186
	v_add_f32_e32 v187, 1.0, v187
	v_rcp_f32_e32 v158, v158
	v_rcp_f32_e32 v159, v159
	v_rcp_f32_e32 v160, v160
	v_rcp_f32_e32 v161, v161
	v_rcp_f32_e32 v168, v168
	v_rcp_f32_e32 v181, v181
	v_rcp_f32_e32 v182, v182
	v_rcp_f32_e32 v188, v154
	v_cvt_pk_bf16_f32 v153, v155, v158
	v_cvt_pk_bf16_f32 v154, v159, v160
	v_cvt_pk_bf16_f32 v155, v161, v168
	global_store_dwordx4 v[156:157], v[152:155], off
	v_rcp_f32_e32 v183, v183
	v_rcp_f32_e32 v184, v184
	v_cvt_pk_bf16_f32 v152, v181, v182
	v_rcp_f32_e32 v185, v185
	v_rcp_f32_e32 v186, v186
	v_rcp_f32_e32 v187, v187
	v_cvt_pk_bf16_f32 v153, v183, v184
	v_cvt_pk_bf16_f32 v154, v185, v186
	v_cvt_pk_bf16_f32 v155, v187, v188
	global_store_dwordx4 v[156:157], v[152:155], off offset:256
	s_nop 1
	v_or_b32_e32 v152, 32, v180
	v_ashrrev_i32_e32 v153, 31, v152
	v_lshl_add_u64 v[154:155], v[152:153], 2, s[40:41]
	s_nop 0
	v_lshlrev_b64 v[152:153], 12, v[152:153]
	v_lshl_add_u64 v[152:153], s[94:95], 0, v[152:153]
	v_lshl_add_u64 v[156:157], v[152:153], 0, v[150:151]
	s_waitcnt vmcnt(7)
	v_mov_b32_e32 v154, v238
	v_fmamk_f32 v154, v154, 0x3a800000, v210
	v_rsq_f32_e32 v154, v154
	s_nop 0
	v_fma_f32 v152, v94, v154, v142
	v_fma_f32 v153, v95, v154, v143
	v_fma_f32 v155, v96, v154, v144
	v_mul_f32_e32 v152, 0xbfb8aa3b, v152
	v_fma_f32 v158, v97, v154, v145
	v_fma_f32 v159, v90, v154, v138
	v_fma_f32 v160, v91, v154, v139
	v_fma_f32 v161, v92, v154, v140
	v_fma_f32 v168, v93, v154, v141
	v_fma_f32 v181, v86, v154, v134
	v_fma_f32 v182, v87, v154, v135
	v_fma_f32 v183, v88, v154, v136
	v_fma_f32 v184, v89, v154, v137
	v_fma_f32 v185, v82, v154, v130
	v_fma_f32 v186, v83, v154, v131
	v_fma_f32 v187, v84, v154, v132
	v_fma_f32 v154, v85, v154, v133
	v_mul_f32_e32 v153, 0xbfb8aa3b, v153
	v_mul_f32_e32 v155, 0xbfb8aa3b, v155
	v_exp_f32_e32 v152, v152
	v_mul_f32_e32 v158, 0xbfb8aa3b, v158
	v_mul_f32_e32 v159, 0xbfb8aa3b, v159
	v_mul_f32_e32 v160, 0xbfb8aa3b, v160
	v_mul_f32_e32 v161, 0xbfb8aa3b, v161
	v_mul_f32_e32 v168, 0xbfb8aa3b, v168
	v_mul_f32_e32 v181, 0xbfb8aa3b, v181
	v_mul_f32_e32 v182, 0xbfb8aa3b, v182
	v_mul_f32_e32 v154, 0xbfb8aa3b, v154
	v_exp_f32_e32 v153, v153
	v_exp_f32_e32 v155, v155
	v_mul_f32_e32 v183, 0xbfb8aa3b, v183
	v_mul_f32_e32 v184, 0xbfb8aa3b, v184
	v_mul_f32_e32 v185, 0xbfb8aa3b, v185
	v_mul_f32_e32 v186, 0xbfb8aa3b, v186
	v_mul_f32_e32 v187, 0xbfb8aa3b, v187
	v_exp_f32_e32 v158, v158
	v_exp_f32_e32 v159, v159
	v_exp_f32_e32 v160, v160
	v_exp_f32_e32 v161, v161
	v_exp_f32_e32 v168, v168
	v_exp_f32_e32 v181, v181
	v_exp_f32_e32 v182, v182
	v_exp_f32_e32 v154, v154
	v_exp_f32_e32 v183, v183
	v_exp_f32_e32 v184, v184
	v_exp_f32_e32 v185, v185
	v_exp_f32_e32 v186, v186
	v_exp_f32_e32 v187, v187
	v_add_f32_e32 v152, 1.0, v152
	v_add_f32_e32 v153, 1.0, v153
	v_add_f32_e32 v155, 1.0, v155
	v_rcp_f32_e32 v152, v152
	v_add_f32_e32 v158, 1.0, v158
	v_add_f32_e32 v159, 1.0, v159
	v_add_f32_e32 v160, 1.0, v160
	v_add_f32_e32 v161, 1.0, v161
	v_add_f32_e32 v168, 1.0, v168
	v_add_f32_e32 v181, 1.0, v181
	v_add_f32_e32 v182, 1.0, v182
	v_add_f32_e32 v154, 1.0, v154
	v_rcp_f32_e32 v153, v153
	v_rcp_f32_e32 v155, v155
	v_cvt_pk_bf16_f32 v152, v152, v153
	v_add_f32_e32 v183, 1.0, v183
	v_add_f32_e32 v184, 1.0, v184
	v_add_f32_e32 v185, 1.0, v185
	v_add_f32_e32 v186, 1.0, v186
	v_add_f32_e32 v187, 1.0, v187
	v_rcp_f32_e32 v158, v158
	v_rcp_f32_e32 v159, v159
	v_rcp_f32_e32 v160, v160
	v_rcp_f32_e32 v161, v161
	v_rcp_f32_e32 v168, v168
	v_rcp_f32_e32 v181, v181
	v_rcp_f32_e32 v182, v182
	v_rcp_f32_e32 v188, v154
	v_cvt_pk_bf16_f32 v153, v155, v158
	v_cvt_pk_bf16_f32 v154, v159, v160
	v_cvt_pk_bf16_f32 v155, v161, v168
	global_store_dwordx4 v[156:157], v[152:155], off
	v_rcp_f32_e32 v183, v183
	v_rcp_f32_e32 v184, v184
	v_cvt_pk_bf16_f32 v152, v181, v182
	v_rcp_f32_e32 v185, v185
	v_rcp_f32_e32 v186, v186
	v_rcp_f32_e32 v187, v187
	v_cvt_pk_bf16_f32 v153, v183, v184
	v_cvt_pk_bf16_f32 v154, v185, v186
	v_cvt_pk_bf16_f32 v155, v187, v188
	global_store_dwordx4 v[156:157], v[152:155], off offset:256
	s_nop 1
	v_or_b32_e32 v152, 48, v180
	v_ashrrev_i32_e32 v153, 31, v152
	v_lshl_add_u64 v[154:155], v[152:153], 2, s[40:41]
	s_nop 0
	v_lshlrev_b64 v[152:153], 12, v[152:153]
	v_lshl_add_u64 v[152:153], s[94:95], 0, v[152:153]
	s_waitcnt vmcnt(7)
; __device__ __forceinline__ unsigned cvt_pk_bf16(float lo, float hi) { unsigned r; asm volatile("v_cvt_pk_bf16_f32 %0, %1, %2" : "=v"(r) : "v"(lo), "v"(hi)); return r; }
; __device__ __forceinline__ float sigmoid_f(float x) { return __builtin_amdgcn_rcpf(1.f + __builtin_amdgcn_exp2f(-1.4426950408889634f * x)); }
;     __device__ __forceinline__ void operator()(const f32x4 (&acc)[2][2][4][2], const Unit& u, int wr, int wc, int fr, int fq) const {
;     ...
;             for (int ai = 0; ai < 2; ++ai)
; #pragma unroll
;                 for (int m = 0; m < 4; ++m) {
;                     const int row = row0 + ai * HALF + m * 16; const float r = __builtin_amdgcn_rsqf(rss[row] * (1.f / 1024.f) + NEPS);
; #pragma unroll
;                     for (int bj = 0; bj < 2; ++bj) {
;                         float o[8];
; #pragma unroll
;                         for (int n = 0; n < 2; ++n)
; #pragma unroll
;                             for (int e = 0; e < 4; ++e) o[4 * n + e] = sigmoid_f(acc[ai][bj][m][n][e] * r + bv[bj][n][e]);
;                         u32x4 w; w.x = cvt_pk_bf16(o[0], o[1]); w.y = cvt_pk_bf16(o[2], o[3]); w.z = cvt_pk_bf16(o[4], o[5]); w.w = cvt_pk_bf16(o[6], o[7]);
;                         *(u32x4*)(G + (size_t)row * 2048 + col0 + bj * HALF) = w;
;                     }
	v_mov_b32_e32 v154, v239
	v_fmamk_f32 v154, v154, 0x3a800000, v210
	v_rsq_f32_e32 v156, v154
	v_lshl_add_u64 v[154:155], v[152:153], 0, v[150:151]
	v_fma_f32 v150, v78, v156, v142
	v_fma_f32 v151, v79, v156, v143
	v_fma_f32 v152, v80, v156, v144
	v_fma_f32 v153, v81, v156, v145
	v_fma_f32 v157, v74, v156, v138
	v_fma_f32 v158, v75, v156, v139
	v_fma_f32 v159, v76, v156, v140
	v_fma_f32 v160, v77, v156, v141
	v_mul_f32_e32 v150, 0xbfb8aa3b, v150
	v_mul_f32_e32 v151, 0xbfb8aa3b, v151
	v_mul_f32_e32 v152, 0xbfb8aa3b, v152
	v_mul_f32_e32 v153, 0xbfb8aa3b, v153
	v_fma_f32 v161, v70, v156, v134
	v_fma_f32 v168, v71, v156, v135
	v_fma_f32 v181, v72, v156, v136
	v_fma_f32 v182, v73, v156, v137
	v_fma_f32 v183, v66, v156, v130
	v_fma_f32 v184, v67, v156, v131
	v_fma_f32 v185, v68, v156, v132
	v_fma_f32 v156, v69, v156, v133
	v_mul_f32_e32 v157, 0xbfb8aa3b, v157
	v_mul_f32_e32 v158, 0xbfb8aa3b, v158
	v_mul_f32_e32 v159, 0xbfb8aa3b, v159
	v_mul_f32_e32 v160, 0xbfb8aa3b, v160
	v_exp_f32_e32 v150, v150
	v_exp_f32_e32 v151, v151
	v_exp_f32_e32 v152, v152
	v_exp_f32_e32 v153, v153
	v_mul_f32_e32 v161, 0xbfb8aa3b, v161
	v_mul_f32_e32 v168, 0xbfb8aa3b, v168
	v_mul_f32_e32 v181, 0xbfb8aa3b, v181
	v_mul_f32_e32 v182, 0xbfb8aa3b, v182
	v_mul_f32_e32 v183, 0xbfb8aa3b, v183
	v_mul_f32_e32 v184, 0xbfb8aa3b, v184
	v_mul_f32_e32 v185, 0xbfb8aa3b, v185
	v_mul_f32_e32 v156, 0xbfb8aa3b, v156
	v_exp_f32_e32 v157, v157
	v_exp_f32_e32 v158, v158
	v_exp_f32_e32 v159, v159
	v_exp_f32_e32 v160, v160
	v_exp_f32_e32 v161, v161
	v_exp_f32_e32 v168, v168
	v_exp_f32_e32 v181, v181
	v_exp_f32_e32 v182, v182
	v_exp_f32_e32 v183, v183
	v_exp_f32_e32 v184, v184
	v_exp_f32_e32 v185, v185
	v_exp_f32_e32 v156, v156
	v_add_f32_e32 v150, 1.0, v150
	v_add_f32_e32 v151, 1.0, v151
	v_add_f32_e32 v152, 1.0, v152
	v_add_f32_e32 v153, 1.0, v153
	v_add_f32_e32 v157, 1.0, v157
	v_add_f32_e32 v158, 1.0, v158
	v_add_f32_e32 v159, 1.0, v159
	v_add_f32_e32 v160, 1.0, v160
	v_rcp_f32_e32 v150, v150
	v_rcp_f32_e32 v151, v151
	v_rcp_f32_e32 v152, v152
	v_rcp_f32_e32 v153, v153
	v_add_f32_e32 v161, 1.0, v161
	v_add_f32_e32 v168, 1.0, v168
	v_add_f32_e32 v181, 1.0, v181
	v_add_f32_e32 v182, 1.0, v182
	v_add_f32_e32 v183, 1.0, v183
	v_add_f32_e32 v184, 1.0, v184
	v_add_f32_e32 v185, 1.0, v185
	v_add_f32_e32 v156, 1.0, v156
	v_rcp_f32_e32 v157, v157
	v_rcp_f32_e32 v158, v158
	v_rcp_f32_e32 v159, v159
	v_rcp_f32_e32 v160, v160
	v_cvt_pk_bf16_f32 v150, v150, v151
	v_cvt_pk_bf16_f32 v151, v152, v153
	v_cvt_pk_bf16_f32 v152, v157, v158
	v_cvt_pk_bf16_f32 v153, v159, v160
	v_rcp_f32_e32 v161, v161
	v_rcp_f32_e32 v168, v168
	v_rcp_f32_e32 v181, v181
	v_rcp_f32_e32 v182, v182
	v_rcp_f32_e32 v183, v183
	v_rcp_f32_e32 v184, v184
	v_rcp_f32_e32 v185, v185
	v_rcp_f32_e32 v156, v156
	global_store_dwordx4 v[154:155], v[150:153], off
	s_nop 1
	v_cvt_pk_bf16_f32 v150, v161, v168
	v_cvt_pk_bf16_f32 v151, v181, v182
	v_cvt_pk_bf16_f32 v152, v183, v184
	v_cvt_pk_bf16_f32 v153, v185, v156
	global_store_dwordx4 v[154:155], v[150:153], off offset:256
	s_nop 0
	v_add_co_u32_e32 v156, vcc, s0, v148
	v_lshl_add_u64 v[154:155], v[148:149], 0, s[2:3]
	s_nop 0
	v_addc_co_u32_e32 v157, vcc, 0, v149, vcc
	s_mov_b32 s0, 0x90000
	s_mov_b64 s[2:3], 0x90000
	s_waitcnt vmcnt(7)
	v_mov_b32_e32 v150, v240
	v_fmamk_f32 v150, v150, 0x3a800000, v210
	v_rsq_f32_e32 v150, v150
	s_nop 0
	v_fma_f32 v151, v62, v150, v142
	v_fma_f32 v152, v63, v150, v143
	v_fma_f32 v153, v64, v150, v144
	v_fma_f32 v158, v65, v150, v145
	v_fma_f32 v159, v58, v150, v138
	v_fma_f32 v160, v59, v150, v139
	v_fma_f32 v161, v60, v150, v140
	v_fma_f32 v168, v61, v150, v141
	v_fma_f32 v181, v54, v150, v134
	v_fma_f32 v182, v55, v150, v135
	v_fma_f32 v183, v56, v150, v136
	v_fma_f32 v184, v57, v150, v137
	v_fma_f32 v185, v50, v150, v130
	v_fma_f32 v186, v51, v150, v131
	v_fma_f32 v187, v52, v150, v132
	v_fma_f32 v150, v53, v150, v133
	v_mul_f32_e32 v151, 0xbfb8aa3b, v151
	v_mul_f32_e32 v152, 0xbfb8aa3b, v152
	v_mul_f32_e32 v153, 0xbfb8aa3b, v153
	v_mul_f32_e32 v158, 0xbfb8aa3b, v158
	v_mul_f32_e32 v159, 0xbfb8aa3b, v159
	v_mul_f32_e32 v160, 0xbfb8aa3b, v160
	v_mul_f32_e32 v161, 0xbfb8aa3b, v161
	v_mul_f32_e32 v168, 0xbfb8aa3b, v168
	v_mul_f32_e32 v150, 0xbfb8aa3b, v150
	v_exp_f32_e32 v151, v151
	v_exp_f32_e32 v152, v152
	v_exp_f32_e32 v153, v153
	v_mul_f32_e32 v181, 0xbfb8aa3b, v181
	v_mul_f32_e32 v182, 0xbfb8aa3b, v182
	v_mul_f32_e32 v183, 0xbfb8aa3b, v183
	v_mul_f32_e32 v184, 0xbfb8aa3b, v184
	v_mul_f32_e32 v185, 0xbfb8aa3b, v185
	v_mul_f32_e32 v186, 0xbfb8aa3b, v186
	v_mul_f32_e32 v187, 0xbfb8aa3b, v187
	v_exp_f32_e32 v158, v158
	v_exp_f32_e32 v159, v159
	v_exp_f32_e32 v160, v160
	v_exp_f32_e32 v161, v161
	v_exp_f32_e32 v168, v168
	v_exp_f32_e32 v150, v150
	v_exp_f32_e32 v181, v181
	v_exp_f32_e32 v182, v182
	v_exp_f32_e32 v183, v183
	v_exp_f32_e32 v184, v184
	v_exp_f32_e32 v185, v185
	v_exp_f32_e32 v186, v186
	v_exp_f32_e32 v187, v187
	v_add_f32_e32 v151, 1.0, v151
	v_add_f32_e32 v152, 1.0, v152
	v_add_f32_e32 v153, 1.0, v153
	v_add_f32_e32 v158, 1.0, v158
	v_add_f32_e32 v159, 1.0, v159
	v_add_f32_e32 v160, 1.0, v160
	v_add_f32_e32 v161, 1.0, v161
	v_add_f32_e32 v168, 1.0, v168
	v_add_f32_e32 v150, 1.0, v150
	v_rcp_f32_e32 v151, v151
	v_rcp_f32_e32 v152, v152
	v_rcp_f32_e32 v153, v153
	v_add_f32_e32 v181, 1.0, v181
	v_add_f32_e32 v182, 1.0, v182
	v_add_f32_e32 v183, 1.0, v183
	v_add_f32_e32 v184, 1.0, v184
	v_add_f32_e32 v185, 1.0, v185
	v_add_f32_e32 v186, 1.0, v186
	v_add_f32_e32 v187, 1.0, v187
	v_rcp_f32_e32 v158, v158
	v_rcp_f32_e32 v159, v159
	v_rcp_f32_e32 v160, v160
	v_rcp_f32_e32 v161, v161
	v_rcp_f32_e32 v168, v168
	v_rcp_f32_e32 v188, v150
	v_cvt_pk_bf16_f32 v150, v151, v152
	v_cvt_pk_bf16_f32 v151, v153, v158
	v_cvt_pk_bf16_f32 v152, v159, v160
	v_cvt_pk_bf16_f32 v153, v161, v168
	v_rcp_f32_e32 v181, v181
	v_rcp_f32_e32 v182, v182
	v_rcp_f32_e32 v183, v183
	v_rcp_f32_e32 v184, v184
	v_rcp_f32_e32 v185, v185
	v_rcp_f32_e32 v186, v186
	v_rcp_f32_e32 v187, v187
	global_store_dwordx4 v[156:157], v[150:153], off
	v_add_co_u32_e32 v156, vcc, s0, v148
	s_nop 0
	v_cvt_pk_bf16_f32 v150, v181, v182
	v_cvt_pk_bf16_f32 v151, v183, v184
	v_cvt_pk_bf16_f32 v152, v185, v186
	v_cvt_pk_bf16_f32 v153, v187, v188
	global_store_dwordx4 v[154:155], v[150:153], off offset:256
	s_nop 0
	v_lshl_add_u64 v[154:155], v[148:149], 0, s[2:3]
	v_addc_co_u32_e32 v157, vcc, 0, v149, vcc
	s_mov_b32 s0, 0xa0000
	s_mov_b64 s[2:3], 0xa0000
	s_waitcnt vmcnt(7)
; __device__ __forceinline__ unsigned cvt_pk_bf16(float lo, float hi) { unsigned r; asm volatile("v_cvt_pk_bf16_f32 %0, %1, %2" : "=v"(r) : "v"(lo), "v"(hi)); return r; }
; __device__ __forceinline__ float sigmoid_f(float x) { return __builtin_amdgcn_rcpf(1.f + __builtin_amdgcn_exp2f(-1.4426950408889634f * x)); }
;     __device__ __forceinline__ void operator()(const f32x4 (&acc)[2][2][4][2], const Unit& u, int wr, int wc, int fr, int fq) const {
;     ...
;             for (int ai = 0; ai < 2; ++ai)
; #pragma unroll
;                 for (int m = 0; m < 4; ++m) {
;                     const int row = row0 + ai * HALF + m * 16; const float r = __builtin_amdgcn_rsqf(rss[row] * (1.f / 1024.f) + NEPS);
; #pragma unroll
;                     for (int bj = 0; bj < 2; ++bj) {
;                         float o[8];
; #pragma unroll
;                         for (int n = 0; n < 2; ++n)
; #pragma unroll
;                             for (int e = 0; e < 4; ++e) o[4 * n + e] = sigmoid_f(acc[ai][bj][m][n][e] * r + bv[bj][n][e]);
;                         u32x4 w; w.x = cvt_pk_bf16(o[0], o[1]); w.y = cvt_pk_bf16(o[2], o[3]); w.z = cvt_pk_bf16(o[4], o[5]); w.w = cvt_pk_bf16(o[6], o[7]);
;                         *(u32x4*)(G + (size_t)row * 2048 + col0 + bj * HALF) = w;
;                     }
	v_mov_b32_e32 v150, v241
	v_fmamk_f32 v150, v150, 0x3a800000, v210
	v_rsq_f32_e32 v150, v150
	s_nop 0
	v_fma_f32 v151, v46, v150, v142
	v_fma_f32 v152, v47, v150, v143
	v_fma_f32 v153, v48, v150, v144
	v_fma_f32 v158, v49, v150, v145
	v_fma_f32 v159, v42, v150, v138
	v_fma_f32 v160, v43, v150, v139
	v_fma_f32 v161, v44, v150, v140
	v_fma_f32 v168, v45, v150, v141
	v_fma_f32 v181, v38, v150, v134
	v_fma_f32 v182, v39, v150, v135
	v_fma_f32 v183, v40, v150, v136
	v_fma_f32 v184, v41, v150, v137
	v_fma_f32 v185, v34, v150, v130
	v_fma_f32 v186, v35, v150, v131
	v_fma_f32 v187, v36, v150, v132
	v_fma_f32 v150, v37, v150, v133
	v_mul_f32_e32 v151, 0xbfb8aa3b, v151
	v_mul_f32_e32 v152, 0xbfb8aa3b, v152
	v_mul_f32_e32 v153, 0xbfb8aa3b, v153
	v_mul_f32_e32 v158, 0xbfb8aa3b, v158
	v_mul_f32_e32 v159, 0xbfb8aa3b, v159
	v_mul_f32_e32 v160, 0xbfb8aa3b, v160
	v_mul_f32_e32 v161, 0xbfb8aa3b, v161
	v_mul_f32_e32 v168, 0xbfb8aa3b, v168
	v_mul_f32_e32 v150, 0xbfb8aa3b, v150
	v_exp_f32_e32 v151, v151
	v_exp_f32_e32 v152, v152
	v_exp_f32_e32 v153, v153
	v_mul_f32_e32 v181, 0xbfb8aa3b, v181
	v_mul_f32_e32 v182, 0xbfb8aa3b, v182
	v_mul_f32_e32 v183, 0xbfb8aa3b, v183
	v_mul_f32_e32 v184, 0xbfb8aa3b, v184
	v_mul_f32_e32 v185, 0xbfb8aa3b, v185
	v_mul_f32_e32 v186, 0xbfb8aa3b, v186
	v_mul_f32_e32 v187, 0xbfb8aa3b, v187
	v_exp_f32_e32 v158, v158
	v_exp_f32_e32 v159, v159
	v_exp_f32_e32 v160, v160
	v_exp_f32_e32 v161, v161
	v_exp_f32_e32 v168, v168
	v_exp_f32_e32 v150, v150
	v_exp_f32_e32 v181, v181
	v_exp_f32_e32 v182, v182
	v_exp_f32_e32 v183, v183
	v_exp_f32_e32 v184, v184
	v_exp_f32_e32 v185, v185
	v_exp_f32_e32 v186, v186
	v_exp_f32_e32 v187, v187
	v_add_f32_e32 v151, 1.0, v151
	v_add_f32_e32 v152, 1.0, v152
	v_add_f32_e32 v153, 1.0, v153
	v_add_f32_e32 v158, 1.0, v158
	v_add_f32_e32 v159, 1.0, v159
	v_add_f32_e32 v160, 1.0, v160
	v_add_f32_e32 v161, 1.0, v161
	v_add_f32_e32 v168, 1.0, v168
	v_add_f32_e32 v150, 1.0, v150
	v_rcp_f32_e32 v151, v151
	v_rcp_f32_e32 v152, v152
	v_rcp_f32_e32 v153, v153
	v_add_f32_e32 v181, 1.0, v181
	v_add_f32_e32 v182, 1.0, v182
	v_add_f32_e32 v183, 1.0, v183
	v_add_f32_e32 v184, 1.0, v184
	v_add_f32_e32 v185, 1.0, v185
	v_add_f32_e32 v186, 1.0, v186
	v_add_f32_e32 v187, 1.0, v187
	v_rcp_f32_e32 v158, v158
	v_rcp_f32_e32 v159, v159
	v_rcp_f32_e32 v160, v160
	v_rcp_f32_e32 v161, v161
	v_rcp_f32_e32 v168, v168
	v_rcp_f32_e32 v188, v150
	v_cvt_pk_bf16_f32 v150, v151, v152
	v_cvt_pk_bf16_f32 v151, v153, v158
	v_cvt_pk_bf16_f32 v152, v159, v160
	v_cvt_pk_bf16_f32 v153, v161, v168
	v_rcp_f32_e32 v181, v181
	v_rcp_f32_e32 v182, v182
	v_rcp_f32_e32 v183, v183
	v_rcp_f32_e32 v184, v184
	v_rcp_f32_e32 v185, v185
	v_rcp_f32_e32 v186, v186
	v_rcp_f32_e32 v187, v187
	global_store_dwordx4 v[156:157], v[150:153], off
	v_add_co_u32_e32 v156, vcc, s0, v148
	s_nop 0
	v_cvt_pk_bf16_f32 v150, v181, v182
	v_cvt_pk_bf16_f32 v151, v183, v184
	v_cvt_pk_bf16_f32 v152, v185, v186
	v_cvt_pk_bf16_f32 v153, v187, v188
	global_store_dwordx4 v[154:155], v[150:153], off offset:256
	s_nop 0
	v_lshl_add_u64 v[154:155], v[148:149], 0, s[2:3]
	v_addc_co_u32_e32 v157, vcc, 0, v149, vcc
	s_mov_b64 s[2:3], 0xb0000
	s_mov_b32 s0, 0xb0000
	s_waitcnt vmcnt(7)
; __device__ __forceinline__ unsigned cvt_pk_bf16(float lo, float hi) { unsigned r; asm volatile("v_cvt_pk_bf16_f32 %0, %1, %2" : "=v"(r) : "v"(lo), "v"(hi)); return r; }
; __device__ __forceinline__ float sigmoid_f(float x) { return __builtin_amdgcn_rcpf(1.f + __builtin_amdgcn_exp2f(-1.4426950408889634f * x)); }
;     __device__ __forceinline__ void operator()(const f32x4 (&acc)[2][2][4][2], const Unit& u, int wr, int wc, int fr, int fq) const {
;     ...
;             for (int ai = 0; ai < 2; ++ai)
; #pragma unroll
;                 for (int m = 0; m < 4; ++m) {
;                     const int row = row0 + ai * HALF + m * 16; const float r = __builtin_amdgcn_rsqf(rss[row] * (1.f / 1024.f) + NEPS);
; #pragma unroll
;                     for (int bj = 0; bj < 2; ++bj) {
;                         float o[8];
; #pragma unroll
;                         for (int n = 0; n < 2; ++n)
; #pragma unroll
;                             for (int e = 0; e < 4; ++e) o[4 * n + e] = sigmoid_f(acc[ai][bj][m][n][e] * r + bv[bj][n][e]);
;                         u32x4 w; w.x = cvt_pk_bf16(o[0], o[1]); w.y = cvt_pk_bf16(o[2], o[3]); w.z = cvt_pk_bf16(o[4], o[5]); w.w = cvt_pk_bf16(o[6], o[7]);
;                         *(u32x4*)(G + (size_t)row * 2048 + col0 + bj * HALF) = w;
;                     }
	v_mov_b32_e32 v150, v242
	v_fmamk_f32 v150, v150, 0x3a800000, v210
	v_rsq_f32_e32 v150, v150
	s_nop 0
	v_fma_f32 v151, v30, v150, v142
	v_fma_f32 v152, v31, v150, v143
	v_fma_f32 v153, v32, v150, v144
	v_fma_f32 v158, v33, v150, v145
	v_fma_f32 v159, v26, v150, v138
	v_fma_f32 v160, v27, v150, v139
	v_fma_f32 v161, v28, v150, v140
	v_fma_f32 v168, v29, v150, v141
	v_fma_f32 v181, v22, v150, v134
	v_fma_f32 v182, v23, v150, v135
	v_fma_f32 v183, v24, v150, v136
	v_fma_f32 v184, v25, v150, v137
	v_fma_f32 v185, v18, v150, v130
	v_fma_f32 v186, v19, v150, v131
	v_fma_f32 v187, v20, v150, v132
	v_fma_f32 v150, v21, v150, v133
	v_mul_f32_e32 v151, 0xbfb8aa3b, v151
	v_mul_f32_e32 v152, 0xbfb8aa3b, v152
	v_mul_f32_e32 v153, 0xbfb8aa3b, v153
	v_mul_f32_e32 v158, 0xbfb8aa3b, v158
	v_mul_f32_e32 v159, 0xbfb8aa3b, v159
	v_mul_f32_e32 v160, 0xbfb8aa3b, v160
	v_mul_f32_e32 v161, 0xbfb8aa3b, v161
	v_mul_f32_e32 v168, 0xbfb8aa3b, v168
	v_mul_f32_e32 v150, 0xbfb8aa3b, v150
	v_exp_f32_e32 v151, v151
	v_exp_f32_e32 v152, v152
	v_exp_f32_e32 v153, v153
	v_mul_f32_e32 v181, 0xbfb8aa3b, v181
	v_mul_f32_e32 v182, 0xbfb8aa3b, v182
	v_mul_f32_e32 v183, 0xbfb8aa3b, v183
	v_mul_f32_e32 v184, 0xbfb8aa3b, v184
	v_mul_f32_e32 v185, 0xbfb8aa3b, v185
	v_mul_f32_e32 v186, 0xbfb8aa3b, v186
	v_mul_f32_e32 v187, 0xbfb8aa3b, v187
	v_exp_f32_e32 v158, v158
	v_exp_f32_e32 v159, v159
	v_exp_f32_e32 v160, v160
	v_exp_f32_e32 v161, v161
	v_exp_f32_e32 v168, v168
	v_exp_f32_e32 v150, v150
	v_exp_f32_e32 v181, v181
	v_exp_f32_e32 v182, v182
	v_exp_f32_e32 v183, v183
	v_exp_f32_e32 v184, v184
	v_exp_f32_e32 v185, v185
	v_exp_f32_e32 v186, v186
	v_exp_f32_e32 v187, v187
	v_add_f32_e32 v151, 1.0, v151
	v_add_f32_e32 v152, 1.0, v152
	v_add_f32_e32 v153, 1.0, v153
	v_add_f32_e32 v158, 1.0, v158
	v_add_f32_e32 v159, 1.0, v159
	v_add_f32_e32 v160, 1.0, v160
	v_add_f32_e32 v161, 1.0, v161
	v_add_f32_e32 v168, 1.0, v168
	v_add_f32_e32 v150, 1.0, v150
	v_rcp_f32_e32 v151, v151
	v_rcp_f32_e32 v152, v152
	v_rcp_f32_e32 v153, v153
	v_add_f32_e32 v181, 1.0, v181
	v_add_f32_e32 v182, 1.0, v182
	v_add_f32_e32 v183, 1.0, v183
	v_add_f32_e32 v184, 1.0, v184
	v_add_f32_e32 v185, 1.0, v185
	v_add_f32_e32 v186, 1.0, v186
	v_add_f32_e32 v187, 1.0, v187
	v_rcp_f32_e32 v158, v158
	v_rcp_f32_e32 v159, v159
	v_rcp_f32_e32 v160, v160
	v_rcp_f32_e32 v161, v161
	v_rcp_f32_e32 v168, v168
	v_rcp_f32_e32 v188, v150
	v_cvt_pk_bf16_f32 v150, v151, v152
	v_cvt_pk_bf16_f32 v151, v153, v158
	v_cvt_pk_bf16_f32 v152, v159, v160
	v_cvt_pk_bf16_f32 v153, v161, v168
	v_rcp_f32_e32 v181, v181
	v_rcp_f32_e32 v182, v182
	v_rcp_f32_e32 v183, v183
	v_rcp_f32_e32 v184, v184
	v_rcp_f32_e32 v185, v185
	v_rcp_f32_e32 v186, v186
	v_rcp_f32_e32 v187, v187
	global_store_dwordx4 v[156:157], v[150:153], off
	s_nop 1
	v_cvt_pk_bf16_f32 v150, v181, v182
	v_cvt_pk_bf16_f32 v151, v183, v184
	v_cvt_pk_bf16_f32 v152, v185, v186
	v_cvt_pk_bf16_f32 v153, v187, v188
	global_store_dwordx4 v[154:155], v[150:153], off offset:256
	s_nop 0
	v_lshl_add_u64 v[146:147], v[148:149], 0, s[2:3]
	v_add_co_u32_e32 v148, vcc, s0, v148
	s_mov_b64 s[2:3], 0
	s_nop 0
	v_addc_co_u32_e32 v149, vcc, 0, v149, vcc
	s_waitcnt vmcnt(7)
	v_mov_b32_e32 v150, v243
	v_fmamk_f32 v150, v150, 0x3a800000, v210
	v_rsq_f32_e32 v150, v150
	s_nop 0
	v_fma_f32 v142, v14, v150, v142
	v_fma_f32 v143, v15, v150, v143
	v_fma_f32 v144, v16, v150, v144
	v_fmac_f32_e32 v145, v17, v150
	v_fma_f32 v138, v10, v150, v138
	v_fma_f32 v139, v11, v150, v139
	v_fma_f32 v140, v12, v150, v140
	v_fmac_f32_e32 v141, v13, v150
	v_fma_f32 v130, v2, v150, v130
	v_fma_f32 v131, v3, v150, v131
	v_fma_f32 v132, v4, v150, v132
	v_fmac_f32_e32 v133, v5, v150
	v_fma_f32 v134, v6, v150, v134
	v_fma_f32 v135, v7, v150, v135
	v_fma_f32 v136, v8, v150, v136
	v_fmac_f32_e32 v137, v9, v150
	v_mul_f32_e32 v142, 0xbfb8aa3b, v142
	v_mul_f32_e32 v143, 0xbfb8aa3b, v143
	v_mul_f32_e32 v144, 0xbfb8aa3b, v144
	v_mul_f32_e32 v145, 0xbfb8aa3b, v145
	v_mul_f32_e32 v138, 0xbfb8aa3b, v138
	v_mul_f32_e32 v139, 0xbfb8aa3b, v139
	v_mul_f32_e32 v140, 0xbfb8aa3b, v140
	v_mul_f32_e32 v141, 0xbfb8aa3b, v141
	v_mul_f32_e32 v130, 0xbfb8aa3b, v130
	v_mul_f32_e32 v131, 0xbfb8aa3b, v131
	v_mul_f32_e32 v132, 0xbfb8aa3b, v132
	v_mul_f32_e32 v133, 0xbfb8aa3b, v133
	v_mul_f32_e32 v134, 0xbfb8aa3b, v134
	v_mul_f32_e32 v135, 0xbfb8aa3b, v135
	v_mul_f32_e32 v136, 0xbfb8aa3b, v136
	v_mul_f32_e32 v137, 0xbfb8aa3b, v137
	v_exp_f32_e32 v142, v142
	v_exp_f32_e32 v143, v143
	v_exp_f32_e32 v144, v144
	v_exp_f32_e32 v145, v145
	v_exp_f32_e32 v138, v138
	v_exp_f32_e32 v139, v139
	v_exp_f32_e32 v140, v140
	v_exp_f32_e32 v141, v141
	v_exp_f32_e32 v130, v130
	v_exp_f32_e32 v131, v131
	v_exp_f32_e32 v132, v132
	v_exp_f32_e32 v133, v133
	v_exp_f32_e32 v134, v134
	v_exp_f32_e32 v135, v135
	v_exp_f32_e32 v136, v136
	v_exp_f32_e32 v137, v137
	v_add_f32_e32 v142, 1.0, v142
	v_add_f32_e32 v143, 1.0, v143
	v_add_f32_e32 v144, 1.0, v144
	v_add_f32_e32 v145, 1.0, v145
	v_add_f32_e32 v138, 1.0, v138
	v_add_f32_e32 v139, 1.0, v139
	v_add_f32_e32 v140, 1.0, v140
	v_add_f32_e32 v141, 1.0, v141
	v_add_f32_e32 v130, 1.0, v130
	v_add_f32_e32 v131, 1.0, v131
	v_add_f32_e32 v132, 1.0, v132
	v_add_f32_e32 v133, 1.0, v133
	v_add_f32_e32 v134, 1.0, v134
	v_add_f32_e32 v135, 1.0, v135
	v_add_f32_e32 v136, 1.0, v136
	v_add_f32_e32 v137, 1.0, v137
	v_rcp_f32_e32 v142, v142
	v_rcp_f32_e32 v143, v143
	v_rcp_f32_e32 v144, v144
	v_rcp_f32_e32 v145, v145
	v_rcp_f32_e32 v138, v138
	v_rcp_f32_e32 v139, v139
	v_rcp_f32_e32 v140, v140
	v_rcp_f32_e32 v141, v141
	v_rcp_f32_e32 v150, v130
	v_rcp_f32_e32 v151, v131
	v_rcp_f32_e32 v152, v132
	v_rcp_f32_e32 v153, v133
	v_cvt_pk_bf16_f32 v130, v142, v143
	v_cvt_pk_bf16_f32 v131, v144, v145
	v_cvt_pk_bf16_f32 v132, v138, v139
	v_cvt_pk_bf16_f32 v133, v140, v141
	v_rcp_f32_e32 v134, v134
	v_rcp_f32_e32 v135, v135
	v_rcp_f32_e32 v136, v136
	v_rcp_f32_e32 v137, v137
	global_store_dwordx4 v[148:149], v[130:133], off
	s_nop 1
	v_cvt_pk_bf16_f32 v130, v134, v135
	v_cvt_pk_bf16_f32 v131, v136, v137
	v_cvt_pk_bf16_f32 v132, v150, v151
	v_cvt_pk_bf16_f32 v133, v152, v153
	global_store_dwordx4 v[146:147], v[130:133], off offset:256

;     __device__ __forceinline__ void operator()(const f32x4 (&acc)[2][2][4][2], const Unit& u, int wr, int wc, int fr, int fq) const {
;     ...
;         } else if (pn < 13) {
;             const int kind = (pn - 4) / 3, g = (pn - 4) % 3;
;             const int W = 128 << (2 * g);
;             const int hcol = (4 * g + wc) * 64;
;             int dim0[2][2];
; #pragma unroll
;             for (int n = 0; n < 2; ++n) { dim0[0][n] = (kind < 2 && fq < 2) ? 4 * fq + 8 * n : 8 * fq + 4 * n; dim0[1][n] = 32 + 8 * fq + 4 * n; }
;             f32x4 gn[2][2];
;             if (kind < 2) { const float* nw = qk_norm + kind * 768 + hcol;
; #pragma unroll
;                 for (int bj = 0; bj < 2; ++bj)
; #pragma unroll
;                     for (int n = 0; n < 2; ++n) gn[bj][n] = *(const f32x4*)(nw + dim0[bj][n]); }
;             bf16_t* dstb = Q + (size_t)kind * ((size_t)16896 * 768);
;             size_t okp = 17301504, oks = 22867968;
;             for (int gg = 0; gg < g; ++gg) { okp += (size_t)2 * 4 * (128 << (2 * gg)) * 256; oks += (size_t)2 * 128 * (128 << (2 * gg)) * 256; }
;             if (kind == 2) { okp += (size_t)4 * W * 256; oks += (size_t)128 * W * 256; }
; #pragma unroll
;             for (int ai = 0; ai < 2; ++ai)
; #pragma unroll
;                 for (int m = 0; m < 4; ++m) {
;                     const int row = row0 + ai * HALF + m * 16; const float r = __builtin_amdgcn_rsqf(rss[row] * (1.f / 1024.f) + NEPS);
;                     f32x4 v[2][2];
; #pragma unroll
;                     for (int bj = 0; bj < 2; ++bj)
; #pragma unroll
;                         for (int n = 0; n < 2; ++n) v[bj][n] = acc[ai][bj][m][n] * r;
;                     int posidx, b, tt; float* cdst = nullptr;
;                     if (!samp) { tt = row & 4095; b = row >> 12; posidx = tt; if (kind >= 1 && tt >= 4096 - W) cdst = out + okp + ((size_t)(b * W + (tt - (4096 - W))) * 4 + wc) * 64; }
;                     else { const int sr = row - 16384; b = sr >> 2; tt = sr & 3; posidx = 4096 + tt; if (kind >= 1) cdst = out + oks + ((size_t)(b * W + (W - 4 + tt)) * 4 + wc) * 64; }
.LBB0_761:
	v_ashrrev_i32_e32 v181, 31, v180
	v_lshl_add_u64 v[188:189], v[180:181], 2, s[40:41]
	global_load_dword v236, v[188:189], off
	global_load_dword v237, v[188:189], off offset:64
	global_load_dword v238, v[188:189], off offset:128
	global_load_dword v239, v[188:189], off offset:192
	global_load_dword v240, v[188:189], off offset:512
	global_load_dword v241, v[188:189], off offset:576
	global_load_dword v242, v[188:189], off offset:640
	global_load_dword v243, v[188:189], off offset:704
	s_lshl_b32 s29, s9, 1
	s_lshl_b32 s0, 0x80, s29
	s_add_i32 s9, s38, -10
	s_lshl_b64 s[2:3], s[0:1], 10
	s_lshl_b64 s[10:11], s[0:1], 15
	s_cmp_lt_u32 s9, 3
	s_cselect_b32 s57, s11, 0
	s_cselect_b32 s56, s10, 0
	s_cselect_b32 s59, s3, 0
	s_cselect_b32 s58, s2, 0
	s_cmp_lt_u32 s8, 3
	s_cselect_b64 s[2:3], -1, 0
	s_cmp_gt_u32 s8, 2
	s_cselect_b64 s[8:9], -1, 0
	s_add_i32 s29, s29, 7
	s_ashr_i32 s10, s27, 12
	s_add_i32 s46, s0, 0xfffff000
	s_lshl_b32 s47, s10, s29
	s_sub_i32 s84, 0x1000, s0
	s_add_i32 s47, s47, s46
	s_mov_b64 s[10:11], -1
	s_and_b64 vcc, exec, s[50:51]
	s_cbranch_vccz .LBB0_763
	v_and_b32_e32 v168, 0xfcf, v180
	v_cmp_gt_u32_e32 vcc, s84, v168
	s_or_b64 s[10:11], s[2:3], vcc
	s_lshl_b64 s[62:63], s[54:55], 2
	s_add_u32 s68, s48, s62
	v_add_u32_e32 v148, s47, v168
	s_addc_u32 s69, s49, s63
	s_lshl_b64 s[62:63], s[58:59], 2
	v_ashrrev_i32_e32 v149, 31, v148
	s_add_u32 s62, s68, s62
	v_lshlrev_b64 v[148:149], 10, v[148:149]
	s_addc_u32 s63, s69, s63
	v_lshl_add_u64 v[148:149], s[62:63], 0, v[148:149]
	s_lshl_b32 s62, s74, 2
	s_mov_b32 s63, s1
	v_lshl_add_u64 v[148:149], v[148:149], 0, s[62:63]
	v_cndmask_b32_e64 v195, v149, 0, s[10:11]
	v_cndmask_b32_e64 v194, v148, 0, s[10:11]
	s_mov_b64 s[10:11], 0

;     __device__ __forceinline__ void operator()(const f32x4 (&acc)[2][2][4][2], const Unit& u, int wr, int wc, int fr, int fq) const {
;     ...
;                     const int row = row0 + ai * HALF + m * 16; const float r = __builtin_amdgcn_rsqf(rss[row] * (1.f / 1024.f) + NEPS);
;                     f32x4 v[2][2];
; #pragma unroll
;                     for (int bj = 0; bj < 2; ++bj)
; #pragma unroll
;                         for (int n = 0; n < 2; ++n) v[bj][n] = acc[ai][bj][m][n] * r;
;                     int posidx, b, tt; float* cdst = nullptr;
;                     if (!samp) { tt = row & 4095; b = row >> 12; posidx = tt; if (kind >= 1 && tt >= 4096 - W) cdst = out + okp + ((size_t)(b * W + (tt - (4096 - W))) * 4 + wc) * 64; }
;                     else { const int sr = row - 16384; b = sr >> 2; tt = sr & 3; posidx = 4096 + tt; if (kind >= 1) cdst = out + oks + ((size_t)(b * W + (W - 4 + tt)) * 4 + wc) * 64; }
;                     if (kind < 2) {
;                         float ss = 0.f;
; #pragma unroll
;                         for (int bj = 0; bj < 2; ++bj)
; #pragma unroll
;                             for (int n = 0; n < 2; ++n) ss += (v[bj][n][0] * v[bj][n][0] + v[bj][n][1] * v[bj][n][1]) + (v[bj][n][2] * v[bj][n][2] + v[bj][n][3] * v[bj][n][3]);
;                         ss += __shfl_xor(ss, 16); ss += __shfl_xor(ss, 32);
;                         const float rn = __builtin_amdgcn_rsqf(ss * (1.f / 64.f) + NEPS);
; #pragma unroll
;                         for (int bj = 0; bj < 2; ++bj)
; #pragma unroll
;                             for (int n = 0; n < 2; ++n) v[bj][n] = v[bj][n] * rn * gn[bj][n];
;                         if (fq < 2) {
;                             const f32x4 cs = *(const f32x4*)(rot + (size_t)posidx * 16 + 4 * fq), sn = *(const f32x4*)(rot + (size_t)posidx * 16 + 8 + 4 * fq);
;                             const f32x4 x1 = v[0][0], x2 = v[0][1];
;                             v[0][0] = x1 * cs - x2 * sn; v[0][1] = x2 * cs + x1 * sn;
.LBB0_767:
	s_waitcnt vmcnt(0)
	v_mov_b32_e32 v146, v236
	v_fmamk_f32 v146, v146, 0x3a800000, v210
	v_rsq_f32_e32 v146, v146
	s_andn2_b64 vcc, exec, s[12:13]
	v_pk_mul_f32 v[160:161], v[128:129], v[146:147] op_sel_hi:[1,0]
	v_pk_mul_f32 v[158:159], v[126:127], v[146:147] op_sel_hi:[1,0]
	v_pk_mul_f32 v[156:157], v[124:125], v[146:147] op_sel_hi:[1,0]
	v_pk_mul_f32 v[154:155], v[122:123], v[146:147] op_sel_hi:[1,0]
	v_pk_mul_f32 v[152:153], v[120:121], v[146:147] op_sel_hi:[1,0]
	v_pk_mul_f32 v[150:151], v[118:119], v[146:147] op_sel_hi:[1,0]
	v_pk_mul_f32 v[148:149], v[116:117], v[146:147] op_sel_hi:[1,0]
	v_cndmask_b32_e64 v147, 0, 1, s[12:13]
	v_cmp_ne_u32_e64 s[10:11], 1, v147
	v_pk_mul_f32 v[146:147], v[114:115], v[146:147] op_sel_hi:[1,0]
	s_cbranch_vccnz .LBB0_772
	v_pk_mul_f32 v[190:191], v[160:161], v[160:161]
	v_pk_mul_f32 v[192:193], v[158:159], v[158:159]
	s_nop 0
	v_pk_mov_b32 v[196:197], v[192:193], v[190:191] op_sel:[1,0]
	v_mov_b32_e32 v193, v191
	v_pk_add_f32 v[190:191], v[196:197], v[192:193]
	v_pk_mul_f32 v[192:193], v[156:157], v[156:157]
	v_pk_add_f32 v[190:191], v[190:191], v[190:191] op_sel_hi:[0,1]
	v_pk_mul_f32 v[196:197], v[154:155], v[154:155]
	v_mul_f32_e32 v190, v150, v150
	v_pk_mov_b32 v[198:199], v[196:197], v[192:193] op_sel:[1,0]
	v_mov_b32_e32 v197, v193
	v_pk_add_f32 v[192:193], v[198:199], v[196:197]
	v_pk_fma_f32 v[196:197], v[150:151], v[150:151], v[190:191] op_sel_hi:[1,1,0]
	v_mul_f32_e32 v190, v152, v152
	v_pk_add_f32 v[192:193], v[192:193], v[192:193] op_sel_hi:[0,1]
	v_pk_fma_f32 v[198:199], v[152:153], v[152:153], v[190:191] op_sel_hi:[1,1,0]
	v_mul_f32_e32 v196, v146, v146
	v_mul_f32_e32 v198, v147, v147
	v_mul_f32_e32 v190, v148, v148
	v_mul_f32_e32 v192, v149, v149
	v_pk_add_f32 v[196:197], v[196:197], v[198:199]
	v_pk_add_f32 v[190:191], v[190:191], v[192:193]
	s_nop 0
	v_pk_add_f32 v[190:191], v[196:197], v[190:191]
	s_nop 0
	v_add_f32_e32 v187, v190, v191
	v_and_b32_e32 v191, 64, v211
	v_xor_b32_e32 v190, 16, v211
	v_add_u32_e32 v191, 64, v191
	v_cmp_lt_i32_e32 vcc, v190, v191
	s_nop 1
	v_cndmask_b32_e32 v190, v211, v190, vcc
	v_lshlrev_b32_e32 v190, 2, v190
	ds_bpermute_b32 v190, v190, v187
	s_waitcnt lgkmcnt(0)
	v_add_f32_e32 v187, v187, v190
	v_xor_b32_e32 v190, 32, v211
	v_cmp_lt_i32_e32 vcc, v190, v191
	s_nop 1
	v_cndmask_b32_e32 v190, v211, v190, vcc
	v_lshlrev_b32_e32 v190, 2, v190
	ds_bpermute_b32 v190, v190, v187
	s_waitcnt lgkmcnt(0)
	v_add_f32_e32 v187, v187, v190
	v_fmamk_f32 v187, v187, 0x3c800000, v210
	v_rsq_f32_e32 v190, v187
	s_nop 0
	v_pk_mul_f32 v[158:159], v[158:159], v[190:191] op_sel_hi:[1,0]
	v_pk_mul_f32 v[160:161], v[160:161], v[190:191] op_sel_hi:[1,0]
	v_pk_mul_f32 v[154:155], v[154:155], v[190:191] op_sel_hi:[1,0]
	v_pk_mul_f32 v[156:157], v[156:157], v[190:191] op_sel_hi:[1,0]
	v_pk_mul_f32 v[160:161], v[144:145], v[160:161]
	v_pk_mul_f32 v[158:159], v[142:143], v[158:159]
	v_pk_mul_f32 v[156:157], v[140:141], v[156:157]
	v_pk_mul_f32 v[154:155], v[138:139], v[154:155]
	s_and_saveexec_b64 s[12:13], s[6:7]
	s_cbranch_execz .LBB0_770
	v_lshlrev_b64 v[192:193], 6, v[168:169]
	v_lshl_add_u64 v[192:193], v[174:175], 0, v[192:193]
	global_load_dwordx4 v[196:199], v[192:193], off offset:32
	global_load_dwordx4 v[214:217], v[192:193], off
	s_waitcnt vmcnt(1)
	v_pk_mul_f32 v[192:193], v[156:157], v[198:199]
	v_pk_mul_f32 v[200:201], v[154:155], v[196:197]
	v_pk_mul_f32 v[198:199], v[160:161], v[198:199]
	v_pk_mul_f32 v[196:197], v[158:159], v[196:197]
	s_waitcnt vmcnt(0)
	v_pk_fma_f32 v[160:161], v[160:161], v[216:217], v[192:193] neg_lo:[0,0,1] neg_hi:[0,0,1]
	v_pk_fma_f32 v[158:159], v[158:159], v[214:215], v[200:201] neg_lo:[0,0,1] neg_hi:[0,0,1]
	v_pk_fma_f32 v[156:157], v[156:157], v[216:217], v[198:199]
	v_pk_fma_f32 v[154:155], v[154:155], v[214:215], v[196:197]

;     __device__ __forceinline__ void operator()(const f32x4 (&acc)[2][2][4][2], const Unit& u, int wr, int wc, int fr, int fq) const {
;     ...
;                     int posidx, b, tt; float* cdst = nullptr;
;                     if (!samp) { tt = row & 4095; b = row >> 12; posidx = tt; if (kind >= 1 && tt >= 4096 - W) cdst = out + okp + ((size_t)(b * W + (tt - (4096 - W))) * 4 + wc) * 64; }
;                     else { const int sr = row - 16384; b = sr >> 2; tt = sr & 3; posidx = 4096 + tt; if (kind >= 1) cdst = out + oks + ((size_t)(b * W + (W - 4 + tt)) * 4 + wc) * 64; }
.LBB0_780:
	s_or_b64 exec, exec, s[12:13]
	v_or_b32_e32 v196, 16, v180
	v_ashrrev_i32_e32 v197, 31, v196
	v_lshl_add_u64 v[146:147], v[196:197], 2, s[40:41]
	s_nop 0
	v_cndmask_b32_e64 v147, 0, 1, s[50:51]
	v_cmp_ne_u32_e64 s[12:13], 1, v147
	s_andn2_b64 vcc, exec, s[50:51]
	s_mov_b64 s[62:63], -1
	s_cbranch_vccnz .LBB0_782
	v_and_b32_e32 v198, 0xfdf, v196
	v_cmp_gt_u32_e32 vcc, s84, v198
	s_or_b64 s[62:63], s[2:3], vcc
	s_lshl_b64 s[68:69], s[54:55], 2
	s_add_u32 s0, s48, s68
	v_add_u32_e32 v148, s47, v198
	s_addc_u32 s85, s49, s69
	s_lshl_b64 s[68:69], s[58:59], 2
	v_ashrrev_i32_e32 v149, 31, v148
	s_add_u32 s68, s0, s68
	v_lshlrev_b64 v[148:149], 10, v[148:149]
	s_addc_u32 s69, s85, s69
	v_lshl_add_u64 v[148:149], s[68:69], 0, v[148:149]
	s_lshl_b32 s0, s74, 2
	v_lshl_add_u64 v[148:149], v[148:149], 0, s[0:1]
	v_cndmask_b32_e64 v195, v149, 0, s[62:63]
	v_cndmask_b32_e64 v194, v148, 0, s[62:63]
	s_mov_b64 s[62:63], 0

;     __device__ __forceinline__ void operator()(const f32x4 (&acc)[2][2][4][2], const Unit& u, int wr, int wc, int fr, int fq) const {
;     ...
;                     const int row = row0 + ai * HALF + m * 16; const float r = __builtin_amdgcn_rsqf(rss[row] * (1.f / 1024.f) + NEPS);
;                     f32x4 v[2][2];
; #pragma unroll
;                     for (int bj = 0; bj < 2; ++bj)
; #pragma unroll
;                         for (int n = 0; n < 2; ++n) v[bj][n] = acc[ai][bj][m][n] * r;
;                     int posidx, b, tt; float* cdst = nullptr;
;                     if (!samp) { tt = row & 4095; b = row >> 12; posidx = tt; if (kind >= 1 && tt >= 4096 - W) cdst = out + okp + ((size_t)(b * W + (tt - (4096 - W))) * 4 + wc) * 64; }
;                     else { const int sr = row - 16384; b = sr >> 2; tt = sr & 3; posidx = 4096 + tt; if (kind >= 1) cdst = out + oks + ((size_t)(b * W + (W - 4 + tt)) * 4 + wc) * 64; }
;                     if (kind < 2) {
;                         float ss = 0.f;
; #pragma unroll
;                         for (int bj = 0; bj < 2; ++bj)
; #pragma unroll
;                             for (int n = 0; n < 2; ++n) ss += (v[bj][n][0] * v[bj][n][0] + v[bj][n][1] * v[bj][n][1]) + (v[bj][n][2] * v[bj][n][2] + v[bj][n][3] * v[bj][n][3]);
;                         ss += __shfl_xor(ss, 16); ss += __shfl_xor(ss, 32);
;                         const float rn = __builtin_amdgcn_rsqf(ss * (1.f / 64.f) + NEPS);
; #pragma unroll
;                         for (int bj = 0; bj < 2; ++bj)
; #pragma unroll
;                             for (int n = 0; n < 2; ++n) v[bj][n] = v[bj][n] * rn * gn[bj][n];
;                         if (fq < 2) {
;                             const f32x4 cs = *(const f32x4*)(rot + (size_t)posidx * 16 + 4 * fq), sn = *(const f32x4*)(rot + (size_t)posidx * 16 + 8 + 4 * fq);
;                             const f32x4 x1 = v[0][0], x2 = v[0][1];
;                             v[0][0] = x1 * cs - x2 * sn; v[0][1] = x2 * cs + x1 * sn;
.LBB0_786:
	s_waitcnt vmcnt(7)
	v_mov_b32_e32 v146, v237
	v_fmamk_f32 v146, v146, 0x3a800000, v210
	v_rsq_f32_e32 v146, v146
	s_and_b64 vcc, exec, s[10:11]
	v_pk_mul_f32 v[160:161], v[112:113], v[146:147] op_sel_hi:[1,0]
	v_pk_mul_f32 v[158:159], v[110:111], v[146:147] op_sel_hi:[1,0]
	v_pk_mul_f32 v[156:157], v[108:109], v[146:147] op_sel_hi:[1,0]
	v_pk_mul_f32 v[154:155], v[106:107], v[146:147] op_sel_hi:[1,0]
	v_pk_mul_f32 v[152:153], v[104:105], v[146:147] op_sel_hi:[1,0]
	v_pk_mul_f32 v[150:151], v[102:103], v[146:147] op_sel_hi:[1,0]
	v_pk_mul_f32 v[148:149], v[100:101], v[146:147] op_sel_hi:[1,0]
	v_pk_mul_f32 v[146:147], v[98:99], v[146:147] op_sel_hi:[1,0]
	s_cbranch_vccnz .LBB0_791
	v_pk_mul_f32 v[200:201], v[160:161], v[160:161]
	v_pk_mul_f32 v[214:215], v[158:159], v[158:159]
	v_and_b32_e32 v187, 64, v211
	v_pk_mov_b32 v[216:217], v[214:215], v[200:201] op_sel:[1,0]
	v_mov_b32_e32 v215, v201
	v_pk_add_f32 v[200:201], v[216:217], v[214:215]
	v_pk_mul_f32 v[214:215], v[156:157], v[156:157]
	v_pk_add_f32 v[200:201], v[200:201], v[200:201] op_sel_hi:[0,1]
	v_pk_mul_f32 v[216:217], v[154:155], v[154:155]
	v_mul_f32_e32 v200, v150, v150
	v_pk_mov_b32 v[218:219], v[216:217], v[214:215] op_sel:[1,0]
	v_mov_b32_e32 v217, v215
	v_pk_add_f32 v[214:215], v[218:219], v[216:217]
	v_pk_fma_f32 v[216:217], v[150:151], v[150:151], v[200:201] op_sel_hi:[1,1,0]
	v_mul_f32_e32 v200, v152, v152
	v_pk_add_f32 v[214:215], v[214:215], v[214:215] op_sel_hi:[0,1]
	v_pk_fma_f32 v[218:219], v[152:153], v[152:153], v[200:201] op_sel_hi:[1,1,0]
	v_mul_f32_e32 v216, v146, v146
	v_mul_f32_e32 v218, v147, v147
	v_mul_f32_e32 v200, v148, v148
	v_mul_f32_e32 v214, v149, v149
	v_xor_b32_e32 v185, 16, v211
	v_add_u32_e32 v187, 64, v187
	v_pk_add_f32 v[216:217], v[216:217], v[218:219]
	v_pk_add_f32 v[200:201], v[200:201], v[214:215]
	v_cmp_lt_i32_e32 vcc, v185, v187
	v_pk_add_f32 v[200:201], v[216:217], v[200:201]
	s_nop 0
	v_cndmask_b32_e32 v185, v211, v185, vcc
	v_add_f32_e32 v183, v200, v201
	v_lshlrev_b32_e32 v185, 2, v185
	ds_bpermute_b32 v185, v185, v183
	s_waitcnt lgkmcnt(0)
	v_add_f32_e32 v183, v183, v185
	v_xor_b32_e32 v185, 32, v211
	v_cmp_lt_i32_e32 vcc, v185, v187
	s_nop 1
	v_cndmask_b32_e32 v185, v211, v185, vcc
	v_lshlrev_b32_e32 v185, 2, v185
	ds_bpermute_b32 v185, v185, v183
	s_waitcnt lgkmcnt(0)
	v_add_f32_e32 v183, v183, v185
	v_fmamk_f32 v183, v183, 0x3c800000, v210
	v_rsq_f32_e32 v200, v183
	s_nop 0
	v_pk_mul_f32 v[158:159], v[158:159], v[200:201] op_sel_hi:[1,0]
	v_pk_mul_f32 v[160:161], v[160:161], v[200:201] op_sel_hi:[1,0]
	v_pk_mul_f32 v[154:155], v[154:155], v[200:201] op_sel_hi:[1,0]
	v_pk_mul_f32 v[156:157], v[156:157], v[200:201] op_sel_hi:[1,0]
	v_pk_mul_f32 v[160:161], v[144:145], v[160:161]
	v_pk_mul_f32 v[158:159], v[142:143], v[158:159]
	v_pk_mul_f32 v[156:157], v[140:141], v[156:157]
	v_pk_mul_f32 v[154:155], v[138:139], v[154:155]
	s_and_saveexec_b64 s[62:63], s[6:7]
	s_cbranch_execz .LBB0_789
	v_mov_b32_e32 v199, v169
	v_lshlrev_b64 v[198:199], 6, v[198:199]
	v_lshl_add_u64 v[198:199], v[174:175], 0, v[198:199]
	global_load_dwordx4 v[214:217], v[198:199], off offset:32
	global_load_dwordx4 v[218:221], v[198:199], off
	s_waitcnt vmcnt(1)
	v_pk_mul_f32 v[198:199], v[156:157], v[216:217]
	v_pk_mul_f32 v[222:223], v[154:155], v[214:215]
	v_pk_mul_f32 v[216:217], v[160:161], v[216:217]
	v_pk_mul_f32 v[214:215], v[158:159], v[214:215]
	s_waitcnt vmcnt(0)
	v_pk_fma_f32 v[160:161], v[160:161], v[220:221], v[198:199] neg_lo:[0,0,1] neg_hi:[0,0,1]
	v_pk_fma_f32 v[158:159], v[158:159], v[218:219], v[222:223] neg_lo:[0,0,1] neg_hi:[0,0,1]
	v_pk_fma_f32 v[156:157], v[156:157], v[220:221], v[216:217]
	v_pk_fma_f32 v[154:155], v[154:155], v[218:219], v[214:215]

;     __device__ __forceinline__ void operator()(const f32x4 (&acc)[2][2][4][2], const Unit& u, int wr, int wc, int fr, int fq) const {
;     ...
;                     int posidx, b, tt; float* cdst = nullptr;
;                     if (!samp) { tt = row & 4095; b = row >> 12; posidx = tt; if (kind >= 1 && tt >= 4096 - W) cdst = out + okp + ((size_t)(b * W + (tt - (4096 - W))) * 4 + wc) * 64; }
;                     else { const int sr = row - 16384; b = sr >> 2; tt = sr & 3; posidx = 4096 + tt; if (kind >= 1) cdst = out + oks + ((size_t)(b * W + (W - 4 + tt)) * 4 + wc) * 64; }
.LBB0_799:
	s_or_b64 exec, exec, s[62:63]
	v_or_b32_e32 v196, 32, v180
	v_ashrrev_i32_e32 v197, 31, v196
	v_lshl_add_u64 v[146:147], v[196:197], 2, s[40:41]
	s_nop 0
	s_and_b64 vcc, exec, s[12:13]
	s_mov_b64 s[62:63], -1
	s_cbranch_vccnz .LBB0_801
	v_and_b32_e32 v198, 0xfef, v196
	v_cmp_gt_u32_e32 vcc, s84, v198
	s_or_b64 s[62:63], s[2:3], vcc
	s_lshl_b64 s[68:69], s[54:55], 2
	s_add_u32 s0, s48, s68
	v_add_u32_e32 v148, s47, v198
	s_addc_u32 s85, s49, s69
	s_lshl_b64 s[68:69], s[58:59], 2
	v_ashrrev_i32_e32 v149, 31, v148
	s_add_u32 s68, s0, s68
	v_lshlrev_b64 v[148:149], 10, v[148:149]
	s_addc_u32 s69, s85, s69
	v_lshl_add_u64 v[148:149], s[68:69], 0, v[148:149]
	s_lshl_b32 s0, s74, 2
	v_lshl_add_u64 v[148:149], v[148:149], 0, s[0:1]
	v_cndmask_b32_e64 v195, v149, 0, s[62:63]
	v_cndmask_b32_e64 v194, v148, 0, s[62:63]
	s_mov_b64 s[62:63], 0

;     __device__ __forceinline__ void operator()(const f32x4 (&acc)[2][2][4][2], const Unit& u, int wr, int wc, int fr, int fq) const {
;     ...
;                     const int row = row0 + ai * HALF + m * 16; const float r = __builtin_amdgcn_rsqf(rss[row] * (1.f / 1024.f) + NEPS);
;                     f32x4 v[2][2];
; #pragma unroll
;                     for (int bj = 0; bj < 2; ++bj)
; #pragma unroll
;                         for (int n = 0; n < 2; ++n) v[bj][n] = acc[ai][bj][m][n] * r;
;                     int posidx, b, tt; float* cdst = nullptr;
;                     if (!samp) { tt = row & 4095; b = row >> 12; posidx = tt; if (kind >= 1 && tt >= 4096 - W) cdst = out + okp + ((size_t)(b * W + (tt - (4096 - W))) * 4 + wc) * 64; }
;                     else { const int sr = row - 16384; b = sr >> 2; tt = sr & 3; posidx = 4096 + tt; if (kind >= 1) cdst = out + oks + ((size_t)(b * W + (W - 4 + tt)) * 4 + wc) * 64; }
;                     if (kind < 2) {
;                         float ss = 0.f;
; #pragma unroll
;                         for (int bj = 0; bj < 2; ++bj)
; #pragma unroll
;                             for (int n = 0; n < 2; ++n) ss += (v[bj][n][0] * v[bj][n][0] + v[bj][n][1] * v[bj][n][1]) + (v[bj][n][2] * v[bj][n][2] + v[bj][n][3] * v[bj][n][3]);
;                         ss += __shfl_xor(ss, 16); ss += __shfl_xor(ss, 32);
;                         const float rn = __builtin_amdgcn_rsqf(ss * (1.f / 64.f) + NEPS);
; #pragma unroll
;                         for (int bj = 0; bj < 2; ++bj)
; #pragma unroll
;                             for (int n = 0; n < 2; ++n) v[bj][n] = v[bj][n] * rn * gn[bj][n];
;                         if (fq < 2) {
;                             const f32x4 cs = *(const f32x4*)(rot + (size_t)posidx * 16 + 4 * fq), sn = *(const f32x4*)(rot + (size_t)posidx * 16 + 8 + 4 * fq);
;                             const f32x4 x1 = v[0][0], x2 = v[0][1];
;                             v[0][0] = x1 * cs - x2 * sn; v[0][1] = x2 * cs + x1 * sn;
.LBB0_805:
	s_waitcnt vmcnt(7)
	v_mov_b32_e32 v146, v238
	v_fmamk_f32 v146, v146, 0x3a800000, v210
	v_rsq_f32_e32 v146, v146
	s_and_b64 vcc, exec, s[10:11]
	v_pk_mul_f32 v[160:161], v[96:97], v[146:147] op_sel_hi:[1,0]
	v_pk_mul_f32 v[158:159], v[94:95], v[146:147] op_sel_hi:[1,0]
	v_pk_mul_f32 v[156:157], v[92:93], v[146:147] op_sel_hi:[1,0]
	v_pk_mul_f32 v[154:155], v[90:91], v[146:147] op_sel_hi:[1,0]
	v_pk_mul_f32 v[152:153], v[88:89], v[146:147] op_sel_hi:[1,0]
	v_pk_mul_f32 v[150:151], v[86:87], v[146:147] op_sel_hi:[1,0]
	v_pk_mul_f32 v[148:149], v[84:85], v[146:147] op_sel_hi:[1,0]
	v_pk_mul_f32 v[146:147], v[82:83], v[146:147] op_sel_hi:[1,0]
	s_cbranch_vccnz .LBB0_810
	v_pk_mul_f32 v[200:201], v[160:161], v[160:161]
	v_pk_mul_f32 v[214:215], v[158:159], v[158:159]
	v_and_b32_e32 v187, 64, v211
	v_pk_mov_b32 v[216:217], v[214:215], v[200:201] op_sel:[1,0]
	v_mov_b32_e32 v215, v201
	v_pk_add_f32 v[200:201], v[216:217], v[214:215]
	v_pk_mul_f32 v[214:215], v[156:157], v[156:157]
	v_pk_add_f32 v[200:201], v[200:201], v[200:201] op_sel_hi:[0,1]
	v_pk_mul_f32 v[216:217], v[154:155], v[154:155]
	v_mul_f32_e32 v200, v150, v150
	v_pk_mov_b32 v[218:219], v[216:217], v[214:215] op_sel:[1,0]
	v_mov_b32_e32 v217, v215
	v_pk_add_f32 v[214:215], v[218:219], v[216:217]
	v_pk_fma_f32 v[216:217], v[150:151], v[150:151], v[200:201] op_sel_hi:[1,1,0]
	v_mul_f32_e32 v200, v152, v152
	v_pk_add_f32 v[214:215], v[214:215], v[214:215] op_sel_hi:[0,1]
	v_pk_fma_f32 v[218:219], v[152:153], v[152:153], v[200:201] op_sel_hi:[1,1,0]
	v_mul_f32_e32 v216, v146, v146
	v_mul_f32_e32 v218, v147, v147
	v_mul_f32_e32 v200, v148, v148
	v_mul_f32_e32 v214, v149, v149
	v_xor_b32_e32 v185, 16, v211
	v_add_u32_e32 v187, 64, v187
	v_pk_add_f32 v[216:217], v[216:217], v[218:219]
	v_pk_add_f32 v[200:201], v[200:201], v[214:215]
	v_cmp_lt_i32_e32 vcc, v185, v187
	v_pk_add_f32 v[200:201], v[216:217], v[200:201]
	s_nop 0
	v_cndmask_b32_e32 v185, v211, v185, vcc
	v_add_f32_e32 v183, v200, v201
	v_lshlrev_b32_e32 v185, 2, v185
	ds_bpermute_b32 v185, v185, v183
	s_waitcnt lgkmcnt(0)
	v_add_f32_e32 v183, v183, v185
	v_xor_b32_e32 v185, 32, v211
	v_cmp_lt_i32_e32 vcc, v185, v187
	s_nop 1
	v_cndmask_b32_e32 v185, v211, v185, vcc
	v_lshlrev_b32_e32 v185, 2, v185
	ds_bpermute_b32 v185, v185, v183
	s_waitcnt lgkmcnt(0)
	v_add_f32_e32 v183, v183, v185
	v_fmamk_f32 v183, v183, 0x3c800000, v210
	v_rsq_f32_e32 v200, v183
	s_nop 0
	v_pk_mul_f32 v[158:159], v[158:159], v[200:201] op_sel_hi:[1,0]
	v_pk_mul_f32 v[160:161], v[160:161], v[200:201] op_sel_hi:[1,0]
	v_pk_mul_f32 v[154:155], v[154:155], v[200:201] op_sel_hi:[1,0]
	v_pk_mul_f32 v[156:157], v[156:157], v[200:201] op_sel_hi:[1,0]
	v_pk_mul_f32 v[160:161], v[144:145], v[160:161]
	v_pk_mul_f32 v[158:159], v[142:143], v[158:159]
	v_pk_mul_f32 v[156:157], v[140:141], v[156:157]
	v_pk_mul_f32 v[154:155], v[138:139], v[154:155]
	s_and_saveexec_b64 s[62:63], s[6:7]
	s_cbranch_execz .LBB0_808
	v_mov_b32_e32 v199, v169
	v_lshlrev_b64 v[198:199], 6, v[198:199]
	v_lshl_add_u64 v[198:199], v[174:175], 0, v[198:199]
	global_load_dwordx4 v[214:217], v[198:199], off offset:32
	global_load_dwordx4 v[218:221], v[198:199], off
	s_waitcnt vmcnt(1)
	v_pk_mul_f32 v[198:199], v[156:157], v[216:217]
	v_pk_mul_f32 v[222:223], v[154:155], v[214:215]
	v_pk_mul_f32 v[216:217], v[160:161], v[216:217]
	v_pk_mul_f32 v[214:215], v[158:159], v[214:215]
	s_waitcnt vmcnt(0)
	v_pk_fma_f32 v[160:161], v[160:161], v[220:221], v[198:199] neg_lo:[0,0,1] neg_hi:[0,0,1]
	v_pk_fma_f32 v[158:159], v[158:159], v[218:219], v[222:223] neg_lo:[0,0,1] neg_hi:[0,0,1]
	v_pk_fma_f32 v[156:157], v[156:157], v[220:221], v[216:217]
	v_pk_fma_f32 v[154:155], v[154:155], v[218:219], v[214:215]

;     __device__ __forceinline__ void operator()(const f32x4 (&acc)[2][2][4][2], const Unit& u, int wr, int wc, int fr, int fq) const {
;     ...
;                     int posidx, b, tt; float* cdst = nullptr;
;                     if (!samp) { tt = row & 4095; b = row >> 12; posidx = tt; if (kind >= 1 && tt >= 4096 - W) cdst = out + okp + ((size_t)(b * W + (tt - (4096 - W))) * 4 + wc) * 64; }
;                     else { const int sr = row - 16384; b = sr >> 2; tt = sr & 3; posidx = 4096 + tt; if (kind >= 1) cdst = out + oks + ((size_t)(b * W + (W - 4 + tt)) * 4 + wc) * 64; }
.LBB0_818:
	s_or_b64 exec, exec, s[62:63]
	v_or_b32_e32 v196, 48, v180
	v_ashrrev_i32_e32 v197, 31, v196
	v_lshl_add_u64 v[146:147], v[196:197], 2, s[40:41]
	s_nop 0
	s_and_b64 vcc, exec, s[12:13]
	s_mov_b64 s[62:63], -1
	s_cbranch_vccnz .LBB0_820
	v_and_b32_e32 v198, 0xfff, v196
	v_cmp_gt_u32_e32 vcc, s84, v198
	s_or_b64 s[62:63], s[2:3], vcc
	s_lshl_b64 s[68:69], s[54:55], 2
	s_add_u32 s0, s48, s68
	v_add_u32_e32 v148, s47, v198
	s_addc_u32 s47, s49, s69
	s_lshl_b64 s[68:69], s[58:59], 2
	v_ashrrev_i32_e32 v149, 31, v148
	s_add_u32 s68, s0, s68
	v_lshlrev_b64 v[148:149], 10, v[148:149]
	s_addc_u32 s69, s47, s69
	v_lshl_add_u64 v[148:149], s[68:69], 0, v[148:149]
	s_lshl_b32 s0, s74, 2
	v_lshl_add_u64 v[148:149], v[148:149], 0, s[0:1]
	v_cndmask_b32_e64 v195, v149, 0, s[62:63]
	v_cndmask_b32_e64 v194, v148, 0, s[62:63]
	s_mov_b64 s[62:63], 0

;     __device__ __forceinline__ void operator()(const f32x4 (&acc)[2][2][4][2], const Unit& u, int wr, int wc, int fr, int fq) const {
;     ...
;                     const int row = row0 + ai * HALF + m * 16; const float r = __builtin_amdgcn_rsqf(rss[row] * (1.f / 1024.f) + NEPS);
;                     f32x4 v[2][2];
; #pragma unroll
;                     for (int bj = 0; bj < 2; ++bj)
; #pragma unroll
;                         for (int n = 0; n < 2; ++n) v[bj][n] = acc[ai][bj][m][n] * r;
;                     int posidx, b, tt; float* cdst = nullptr;
;                     if (!samp) { tt = row & 4095; b = row >> 12; posidx = tt; if (kind >= 1 && tt >= 4096 - W) cdst = out + okp + ((size_t)(b * W + (tt - (4096 - W))) * 4 + wc) * 64; }
;                     else { const int sr = row - 16384; b = sr >> 2; tt = sr & 3; posidx = 4096 + tt; if (kind >= 1) cdst = out + oks + ((size_t)(b * W + (W - 4 + tt)) * 4 + wc) * 64; }
;                     if (kind < 2) {
;                         float ss = 0.f;
; #pragma unroll
;                         for (int bj = 0; bj < 2; ++bj)
; #pragma unroll
;                             for (int n = 0; n < 2; ++n) ss += (v[bj][n][0] * v[bj][n][0] + v[bj][n][1] * v[bj][n][1]) + (v[bj][n][2] * v[bj][n][2] + v[bj][n][3] * v[bj][n][3]);
;                         ss += __shfl_xor(ss, 16); ss += __shfl_xor(ss, 32);
;                         const float rn = __builtin_amdgcn_rsqf(ss * (1.f / 64.f) + NEPS);
; #pragma unroll
;                         for (int bj = 0; bj < 2; ++bj)
; #pragma unroll
;                             for (int n = 0; n < 2; ++n) v[bj][n] = v[bj][n] * rn * gn[bj][n];
;                         if (fq < 2) {
;                             const f32x4 cs = *(const f32x4*)(rot + (size_t)posidx * 16 + 4 * fq), sn = *(const f32x4*)(rot + (size_t)posidx * 16 + 8 + 4 * fq);
;                             const f32x4 x1 = v[0][0], x2 = v[0][1];
;                             v[0][0] = x1 * cs - x2 * sn; v[0][1] = x2 * cs + x1 * sn;
.LBB0_824:
	s_waitcnt vmcnt(7)
	v_mov_b32_e32 v146, v239
	v_fmamk_f32 v146, v146, 0x3a800000, v210
	v_rsq_f32_e32 v146, v146
	s_and_b64 vcc, exec, s[10:11]
	v_pk_mul_f32 v[160:161], v[80:81], v[146:147] op_sel_hi:[1,0]
	v_pk_mul_f32 v[158:159], v[78:79], v[146:147] op_sel_hi:[1,0]
	v_pk_mul_f32 v[156:157], v[76:77], v[146:147] op_sel_hi:[1,0]
	v_pk_mul_f32 v[154:155], v[74:75], v[146:147] op_sel_hi:[1,0]
	v_pk_mul_f32 v[152:153], v[72:73], v[146:147] op_sel_hi:[1,0]
	v_pk_mul_f32 v[150:151], v[70:71], v[146:147] op_sel_hi:[1,0]
	v_pk_mul_f32 v[148:149], v[68:69], v[146:147] op_sel_hi:[1,0]
	v_pk_mul_f32 v[146:147], v[66:67], v[146:147] op_sel_hi:[1,0]
	s_cbranch_vccnz .LBB0_829
	v_pk_mul_f32 v[200:201], v[160:161], v[160:161]
	v_pk_mul_f32 v[214:215], v[158:159], v[158:159]
	v_and_b32_e32 v187, 64, v211
	v_pk_mov_b32 v[216:217], v[214:215], v[200:201] op_sel:[1,0]
	v_mov_b32_e32 v215, v201
	v_pk_add_f32 v[200:201], v[216:217], v[214:215]
	v_pk_mul_f32 v[214:215], v[156:157], v[156:157]
	v_pk_add_f32 v[200:201], v[200:201], v[200:201] op_sel_hi:[0,1]
	v_pk_mul_f32 v[216:217], v[154:155], v[154:155]
	v_mul_f32_e32 v200, v150, v150
	v_pk_mov_b32 v[218:219], v[216:217], v[214:215] op_sel:[1,0]
	v_mov_b32_e32 v217, v215
	v_pk_add_f32 v[214:215], v[218:219], v[216:217]
	v_pk_fma_f32 v[216:217], v[150:151], v[150:151], v[200:201] op_sel_hi:[1,1,0]
	v_mul_f32_e32 v200, v152, v152
	v_pk_add_f32 v[214:215], v[214:215], v[214:215] op_sel_hi:[0,1]
	v_pk_fma_f32 v[218:219], v[152:153], v[152:153], v[200:201] op_sel_hi:[1,1,0]
	v_mul_f32_e32 v216, v146, v146
	v_mul_f32_e32 v218, v147, v147
	v_mul_f32_e32 v200, v148, v148
	v_mul_f32_e32 v214, v149, v149
	v_xor_b32_e32 v185, 16, v211
	v_add_u32_e32 v187, 64, v187
	v_pk_add_f32 v[216:217], v[216:217], v[218:219]
	v_pk_add_f32 v[200:201], v[200:201], v[214:215]
	v_cmp_lt_i32_e32 vcc, v185, v187
	v_pk_add_f32 v[200:201], v[216:217], v[200:201]
	s_nop 0
	v_cndmask_b32_e32 v185, v211, v185, vcc
	v_add_f32_e32 v183, v200, v201
	v_lshlrev_b32_e32 v185, 2, v185
	ds_bpermute_b32 v185, v185, v183
	s_waitcnt lgkmcnt(0)
	v_add_f32_e32 v183, v183, v185
	v_xor_b32_e32 v185, 32, v211
	v_cmp_lt_i32_e32 vcc, v185, v187
	s_nop 1
	v_cndmask_b32_e32 v185, v211, v185, vcc
	v_lshlrev_b32_e32 v185, 2, v185
	ds_bpermute_b32 v185, v185, v183
	s_waitcnt lgkmcnt(0)
	v_add_f32_e32 v183, v183, v185
	v_fmamk_f32 v183, v183, 0x3c800000, v210
	v_rsq_f32_e32 v200, v183
	s_nop 0
	v_pk_mul_f32 v[158:159], v[158:159], v[200:201] op_sel_hi:[1,0]
	v_pk_mul_f32 v[160:161], v[160:161], v[200:201] op_sel_hi:[1,0]
	v_pk_mul_f32 v[154:155], v[154:155], v[200:201] op_sel_hi:[1,0]
	v_pk_mul_f32 v[156:157], v[156:157], v[200:201] op_sel_hi:[1,0]
	v_pk_mul_f32 v[160:161], v[144:145], v[160:161]
	v_pk_mul_f32 v[158:159], v[142:143], v[158:159]
	v_pk_mul_f32 v[156:157], v[140:141], v[156:157]
	v_pk_mul_f32 v[154:155], v[138:139], v[154:155]
	s_and_saveexec_b64 s[62:63], s[6:7]
	s_cbranch_execz .LBB0_827
	v_mov_b32_e32 v199, v169
	v_lshlrev_b64 v[198:199], 6, v[198:199]
	v_lshl_add_u64 v[198:199], v[174:175], 0, v[198:199]
	global_load_dwordx4 v[214:217], v[198:199], off offset:32
	global_load_dwordx4 v[218:221], v[198:199], off
	s_waitcnt vmcnt(1)
	v_pk_mul_f32 v[198:199], v[156:157], v[216:217]
	v_pk_mul_f32 v[222:223], v[154:155], v[214:215]
	v_pk_mul_f32 v[216:217], v[160:161], v[216:217]
	v_pk_mul_f32 v[214:215], v[158:159], v[214:215]
	s_waitcnt vmcnt(0)
	v_pk_fma_f32 v[160:161], v[160:161], v[220:221], v[198:199] neg_lo:[0,0,1] neg_hi:[0,0,1]
	v_pk_fma_f32 v[158:159], v[158:159], v[218:219], v[222:223] neg_lo:[0,0,1] neg_hi:[0,0,1]
	v_pk_fma_f32 v[156:157], v[156:157], v[220:221], v[216:217]
	v_pk_fma_f32 v[154:155], v[154:155], v[218:219], v[214:215]

;     __device__ __forceinline__ void operator()(const f32x4 (&acc)[2][2][4][2], const Unit& u, int wr, int wc, int fr, int fq) const {
;     ...
;                     int posidx, b, tt; float* cdst = nullptr;
;                     if (!samp) { tt = row & 4095; b = row >> 12; posidx = tt; if (kind >= 1 && tt >= 4096 - W) cdst = out + okp + ((size_t)(b * W + (tt - (4096 - W))) * 4 + wc) * 64; }
;                     else { const int sr = row - 16384; b = sr >> 2; tt = sr & 3; posidx = 4096 + tt; if (kind >= 1) cdst = out + oks + ((size_t)(b * W + (W - 4 + tt)) * 4 + wc) * 64; }
.LBB0_837:
	s_or_b64 exec, exec, s[62:63]
	s_nop 0
	v_add_u32_e32 v196, 0x80, v180
	v_ashrrev_i32_e32 v147, 12, v196
	v_lshlrev_b32_e32 v147, s29, v147
	v_add_u32_e32 v213, s46, v147
	s_and_b64 vcc, exec, s[12:13]
	s_mov_b64 s[62:63], -1
	s_cbranch_vccnz .LBB0_839
	v_and_b32_e32 v198, 0xfcf, v196
	v_cmp_gt_u32_e32 vcc, s84, v198
	s_or_b64 s[46:47], s[2:3], vcc
	s_lshl_b64 s[62:63], s[54:55], 2
	s_add_u32 s0, s48, s62
	v_add_u32_e32 v148, v213, v198
	s_addc_u32 s68, s49, s63
	s_lshl_b64 s[62:63], s[58:59], 2
	v_ashrrev_i32_e32 v149, 31, v148
	s_add_u32 s62, s0, s62
	v_lshlrev_b64 v[148:149], 10, v[148:149]
	s_addc_u32 s63, s68, s63
	v_lshl_add_u64 v[148:149], s[62:63], 0, v[148:149]
	s_lshl_b32 s0, s74, 2
	v_lshl_add_u64 v[148:149], v[148:149], 0, s[0:1]
	v_cndmask_b32_e64 v195, v149, 0, s[46:47]
	v_cndmask_b32_e64 v194, v148, 0, s[46:47]
	s_mov_b64 s[62:63], 0

;     __device__ __forceinline__ void operator()(const f32x4 (&acc)[2][2][4][2], const Unit& u, int wr, int wc, int fr, int fq) const {
;     ...
;                     const int row = row0 + ai * HALF + m * 16; const float r = __builtin_amdgcn_rsqf(rss[row] * (1.f / 1024.f) + NEPS);
;                     f32x4 v[2][2];
; #pragma unroll
;                     for (int bj = 0; bj < 2; ++bj)
; #pragma unroll
;                         for (int n = 0; n < 2; ++n) v[bj][n] = acc[ai][bj][m][n] * r;
;                     int posidx, b, tt; float* cdst = nullptr;
;                     if (!samp) { tt = row & 4095; b = row >> 12; posidx = tt; if (kind >= 1 && tt >= 4096 - W) cdst = out + okp + ((size_t)(b * W + (tt - (4096 - W))) * 4 + wc) * 64; }
;                     else { const int sr = row - 16384; b = sr >> 2; tt = sr & 3; posidx = 4096 + tt; if (kind >= 1) cdst = out + oks + ((size_t)(b * W + (W - 4 + tt)) * 4 + wc) * 64; }
;                     if (kind < 2) {
;                         float ss = 0.f;
; #pragma unroll
;                         for (int bj = 0; bj < 2; ++bj)
; #pragma unroll
;                             for (int n = 0; n < 2; ++n) ss += (v[bj][n][0] * v[bj][n][0] + v[bj][n][1] * v[bj][n][1]) + (v[bj][n][2] * v[bj][n][2] + v[bj][n][3] * v[bj][n][3]);
;                         ss += __shfl_xor(ss, 16); ss += __shfl_xor(ss, 32);
;                         const float rn = __builtin_amdgcn_rsqf(ss * (1.f / 64.f) + NEPS);
; #pragma unroll
;                         for (int bj = 0; bj < 2; ++bj)
; #pragma unroll
;                             for (int n = 0; n < 2; ++n) v[bj][n] = v[bj][n] * rn * gn[bj][n];
;                         if (fq < 2) {
;                             const f32x4 cs = *(const f32x4*)(rot + (size_t)posidx * 16 + 4 * fq), sn = *(const f32x4*)(rot + (size_t)posidx * 16 + 8 + 4 * fq);
;                             const f32x4 x1 = v[0][0], x2 = v[0][1];
;                             v[0][0] = x1 * cs - x2 * sn; v[0][1] = x2 * cs + x1 * sn;
.LBB0_843:
	s_waitcnt vmcnt(7)
	v_mov_b32_e32 v146, v240
	v_fmamk_f32 v146, v146, 0x3a800000, v210
	v_rsq_f32_e32 v146, v146
	s_and_b64 vcc, exec, s[10:11]
	v_pk_mul_f32 v[160:161], v[64:65], v[146:147] op_sel_hi:[1,0]
	v_pk_mul_f32 v[158:159], v[62:63], v[146:147] op_sel_hi:[1,0]
	v_pk_mul_f32 v[156:157], v[60:61], v[146:147] op_sel_hi:[1,0]
	v_pk_mul_f32 v[154:155], v[58:59], v[146:147] op_sel_hi:[1,0]
	v_pk_mul_f32 v[152:153], v[56:57], v[146:147] op_sel_hi:[1,0]
	v_pk_mul_f32 v[150:151], v[54:55], v[146:147] op_sel_hi:[1,0]
	v_pk_mul_f32 v[148:149], v[52:53], v[146:147] op_sel_hi:[1,0]
	v_pk_mul_f32 v[146:147], v[50:51], v[146:147] op_sel_hi:[1,0]
	s_cbranch_vccnz .LBB0_848
	v_pk_mul_f32 v[200:201], v[160:161], v[160:161]
	v_pk_mul_f32 v[214:215], v[158:159], v[158:159]
	v_and_b32_e32 v187, 64, v211
	v_pk_mov_b32 v[216:217], v[214:215], v[200:201] op_sel:[1,0]
	v_mov_b32_e32 v215, v201
	v_pk_add_f32 v[200:201], v[216:217], v[214:215]
	v_pk_mul_f32 v[214:215], v[156:157], v[156:157]
	v_pk_add_f32 v[200:201], v[200:201], v[200:201] op_sel_hi:[0,1]
	v_pk_mul_f32 v[216:217], v[154:155], v[154:155]
	v_mul_f32_e32 v200, v150, v150
	v_pk_mov_b32 v[218:219], v[216:217], v[214:215] op_sel:[1,0]
	v_mov_b32_e32 v217, v215
	v_pk_add_f32 v[214:215], v[218:219], v[216:217]
	v_pk_fma_f32 v[216:217], v[150:151], v[150:151], v[200:201] op_sel_hi:[1,1,0]
	v_mul_f32_e32 v200, v152, v152
	v_pk_add_f32 v[214:215], v[214:215], v[214:215] op_sel_hi:[0,1]
	v_pk_fma_f32 v[218:219], v[152:153], v[152:153], v[200:201] op_sel_hi:[1,1,0]
	v_mul_f32_e32 v216, v146, v146
	v_mul_f32_e32 v218, v147, v147
	v_mul_f32_e32 v200, v148, v148
	v_mul_f32_e32 v214, v149, v149
	v_xor_b32_e32 v185, 16, v211
	v_add_u32_e32 v187, 64, v187
	v_pk_add_f32 v[216:217], v[216:217], v[218:219]
	v_pk_add_f32 v[200:201], v[200:201], v[214:215]
	v_cmp_lt_i32_e32 vcc, v185, v187
	v_pk_add_f32 v[200:201], v[216:217], v[200:201]
	s_nop 0
	v_cndmask_b32_e32 v185, v211, v185, vcc
	v_add_f32_e32 v183, v200, v201
	v_lshlrev_b32_e32 v185, 2, v185
	ds_bpermute_b32 v185, v185, v183
	s_waitcnt lgkmcnt(0)
	v_add_f32_e32 v183, v183, v185
	v_xor_b32_e32 v185, 32, v211
	v_cmp_lt_i32_e32 vcc, v185, v187
	s_nop 1
	v_cndmask_b32_e32 v185, v211, v185, vcc
	v_lshlrev_b32_e32 v185, 2, v185
	ds_bpermute_b32 v185, v185, v183
	s_waitcnt lgkmcnt(0)
	v_add_f32_e32 v183, v183, v185
	v_fmamk_f32 v183, v183, 0x3c800000, v210
	v_rsq_f32_e32 v200, v183
	s_nop 0
	v_pk_mul_f32 v[158:159], v[158:159], v[200:201] op_sel_hi:[1,0]
	v_pk_mul_f32 v[160:161], v[160:161], v[200:201] op_sel_hi:[1,0]
	v_pk_mul_f32 v[154:155], v[154:155], v[200:201] op_sel_hi:[1,0]
	v_pk_mul_f32 v[156:157], v[156:157], v[200:201] op_sel_hi:[1,0]
	v_pk_mul_f32 v[160:161], v[144:145], v[160:161]
	v_pk_mul_f32 v[158:159], v[142:143], v[158:159]
	v_pk_mul_f32 v[156:157], v[140:141], v[156:157]
	v_pk_mul_f32 v[154:155], v[138:139], v[154:155]
	s_and_saveexec_b64 s[62:63], s[6:7]
	s_cbranch_execz .LBB0_846
	v_mov_b32_e32 v199, v169
	v_lshlrev_b64 v[198:199], 6, v[198:199]
	v_lshl_add_u64 v[198:199], v[174:175], 0, v[198:199]
	global_load_dwordx4 v[214:217], v[198:199], off offset:32
	global_load_dwordx4 v[218:221], v[198:199], off
	s_waitcnt vmcnt(1)
	v_pk_mul_f32 v[198:199], v[156:157], v[216:217]
	v_pk_mul_f32 v[222:223], v[154:155], v[214:215]
	v_pk_mul_f32 v[216:217], v[160:161], v[216:217]
	v_pk_mul_f32 v[214:215], v[158:159], v[214:215]
	s_waitcnt vmcnt(0)
	v_pk_fma_f32 v[160:161], v[160:161], v[220:221], v[198:199] neg_lo:[0,0,1] neg_hi:[0,0,1]
	v_pk_fma_f32 v[158:159], v[158:159], v[218:219], v[222:223] neg_lo:[0,0,1] neg_hi:[0,0,1]
	v_pk_fma_f32 v[156:157], v[156:157], v[220:221], v[216:217]
	v_pk_fma_f32 v[154:155], v[154:155], v[218:219], v[214:215]

;     __device__ __forceinline__ void operator()(const f32x4 (&acc)[2][2][4][2], const Unit& u, int wr, int wc, int fr, int fq) const {
;     ...
;                     int posidx, b, tt; float* cdst = nullptr;
;                     if (!samp) { tt = row & 4095; b = row >> 12; posidx = tt; if (kind >= 1 && tt >= 4096 - W) cdst = out + okp + ((size_t)(b * W + (tt - (4096 - W))) * 4 + wc) * 64; }
;                     else { const int sr = row - 16384; b = sr >> 2; tt = sr & 3; posidx = 4096 + tt; if (kind >= 1) cdst = out + oks + ((size_t)(b * W + (W - 4 + tt)) * 4 + wc) * 64; }
.LBB0_856:
	s_or_b64 exec, exec, s[62:63]
	s_nop 0
	v_add_u32_e32 v196, 0x90, v180
	s_and_b64 vcc, exec, s[12:13]
	s_mov_b64 s[62:63], -1
	s_cbranch_vccnz .LBB0_858
	v_and_b32_e32 v198, 0xfdf, v196
	v_cmp_gt_u32_e32 vcc, s84, v198
	s_or_b64 s[46:47], s[2:3], vcc
	s_lshl_b64 s[62:63], s[54:55], 2
	s_add_u32 s0, s48, s62
	v_add_u32_e32 v148, v213, v198
	s_addc_u32 s68, s49, s63
	s_lshl_b64 s[62:63], s[58:59], 2
	v_ashrrev_i32_e32 v149, 31, v148
	s_add_u32 s62, s0, s62
	v_lshlrev_b64 v[148:149], 10, v[148:149]
	s_addc_u32 s63, s68, s63
	v_lshl_add_u64 v[148:149], s[62:63], 0, v[148:149]
	s_lshl_b32 s0, s74, 2
	v_lshl_add_u64 v[148:149], v[148:149], 0, s[0:1]
	v_cndmask_b32_e64 v195, v149, 0, s[46:47]
	v_cndmask_b32_e64 v194, v148, 0, s[46:47]
	s_mov_b64 s[62:63], 0

;     __device__ __forceinline__ void operator()(const f32x4 (&acc)[2][2][4][2], const Unit& u, int wr, int wc, int fr, int fq) const {
;     ...
;                     const int row = row0 + ai * HALF + m * 16; const float r = __builtin_amdgcn_rsqf(rss[row] * (1.f / 1024.f) + NEPS);
;                     f32x4 v[2][2];
; #pragma unroll
;                     for (int bj = 0; bj < 2; ++bj)
; #pragma unroll
;                         for (int n = 0; n < 2; ++n) v[bj][n] = acc[ai][bj][m][n] * r;
;                     int posidx, b, tt; float* cdst = nullptr;
;                     if (!samp) { tt = row & 4095; b = row >> 12; posidx = tt; if (kind >= 1 && tt >= 4096 - W) cdst = out + okp + ((size_t)(b * W + (tt - (4096 - W))) * 4 + wc) * 64; }
;                     else { const int sr = row - 16384; b = sr >> 2; tt = sr & 3; posidx = 4096 + tt; if (kind >= 1) cdst = out + oks + ((size_t)(b * W + (W - 4 + tt)) * 4 + wc) * 64; }
;                     if (kind < 2) {
;                         float ss = 0.f;
; #pragma unroll
;                         for (int bj = 0; bj < 2; ++bj)
; #pragma unroll
;                             for (int n = 0; n < 2; ++n) ss += (v[bj][n][0] * v[bj][n][0] + v[bj][n][1] * v[bj][n][1]) + (v[bj][n][2] * v[bj][n][2] + v[bj][n][3] * v[bj][n][3]);
;                         ss += __shfl_xor(ss, 16); ss += __shfl_xor(ss, 32);
;                         const float rn = __builtin_amdgcn_rsqf(ss * (1.f / 64.f) + NEPS);
; #pragma unroll
;                         for (int bj = 0; bj < 2; ++bj)
; #pragma unroll
;                             for (int n = 0; n < 2; ++n) v[bj][n] = v[bj][n] * rn * gn[bj][n];
;                         if (fq < 2) {
;                             const f32x4 cs = *(const f32x4*)(rot + (size_t)posidx * 16 + 4 * fq), sn = *(const f32x4*)(rot + (size_t)posidx * 16 + 8 + 4 * fq);
;                             const f32x4 x1 = v[0][0], x2 = v[0][1];
;                             v[0][0] = x1 * cs - x2 * sn; v[0][1] = x2 * cs + x1 * sn;
.LBB0_862:
	s_waitcnt vmcnt(7)
	v_mov_b32_e32 v146, v241
	v_fmamk_f32 v146, v146, 0x3a800000, v210
	v_rsq_f32_e32 v146, v146
	s_and_b64 vcc, exec, s[10:11]
	v_pk_mul_f32 v[160:161], v[48:49], v[146:147] op_sel_hi:[1,0]
	v_pk_mul_f32 v[158:159], v[46:47], v[146:147] op_sel_hi:[1,0]
	v_pk_mul_f32 v[156:157], v[44:45], v[146:147] op_sel_hi:[1,0]
	v_pk_mul_f32 v[154:155], v[42:43], v[146:147] op_sel_hi:[1,0]
	v_pk_mul_f32 v[152:153], v[40:41], v[146:147] op_sel_hi:[1,0]
	v_pk_mul_f32 v[150:151], v[38:39], v[146:147] op_sel_hi:[1,0]
	v_pk_mul_f32 v[148:149], v[36:37], v[146:147] op_sel_hi:[1,0]
	v_pk_mul_f32 v[146:147], v[34:35], v[146:147] op_sel_hi:[1,0]
	s_cbranch_vccnz .LBB0_867
	v_pk_mul_f32 v[200:201], v[160:161], v[160:161]
	v_pk_mul_f32 v[214:215], v[158:159], v[158:159]
	v_and_b32_e32 v187, 64, v211
	v_pk_mov_b32 v[216:217], v[214:215], v[200:201] op_sel:[1,0]
	v_mov_b32_e32 v215, v201
	v_pk_add_f32 v[200:201], v[216:217], v[214:215]
	v_pk_mul_f32 v[214:215], v[156:157], v[156:157]
	v_pk_add_f32 v[200:201], v[200:201], v[200:201] op_sel_hi:[0,1]
	v_pk_mul_f32 v[216:217], v[154:155], v[154:155]
	v_mul_f32_e32 v200, v150, v150
	v_pk_mov_b32 v[218:219], v[216:217], v[214:215] op_sel:[1,0]
	v_mov_b32_e32 v217, v215
	v_pk_add_f32 v[214:215], v[218:219], v[216:217]
	v_pk_fma_f32 v[216:217], v[150:151], v[150:151], v[200:201] op_sel_hi:[1,1,0]
	v_mul_f32_e32 v200, v152, v152
	v_pk_add_f32 v[214:215], v[214:215], v[214:215] op_sel_hi:[0,1]
	v_pk_fma_f32 v[218:219], v[152:153], v[152:153], v[200:201] op_sel_hi:[1,1,0]
	v_mul_f32_e32 v216, v146, v146
	v_mul_f32_e32 v218, v147, v147
	v_mul_f32_e32 v200, v148, v148
	v_mul_f32_e32 v214, v149, v149
	v_xor_b32_e32 v185, 16, v211
	v_add_u32_e32 v187, 64, v187
	v_pk_add_f32 v[216:217], v[216:217], v[218:219]
	v_pk_add_f32 v[200:201], v[200:201], v[214:215]
	v_cmp_lt_i32_e32 vcc, v185, v187
	v_pk_add_f32 v[200:201], v[216:217], v[200:201]
	s_nop 0
	v_cndmask_b32_e32 v185, v211, v185, vcc
	v_add_f32_e32 v183, v200, v201
	v_lshlrev_b32_e32 v185, 2, v185
	ds_bpermute_b32 v185, v185, v183
	s_waitcnt lgkmcnt(0)
	v_add_f32_e32 v183, v183, v185
	v_xor_b32_e32 v185, 32, v211
	v_cmp_lt_i32_e32 vcc, v185, v187
	s_nop 1
	v_cndmask_b32_e32 v185, v211, v185, vcc
	v_lshlrev_b32_e32 v185, 2, v185
	ds_bpermute_b32 v185, v185, v183
	s_waitcnt lgkmcnt(0)
	v_add_f32_e32 v183, v183, v185
	v_fmamk_f32 v183, v183, 0x3c800000, v210
	v_rsq_f32_e32 v200, v183
	s_nop 0
	v_pk_mul_f32 v[158:159], v[158:159], v[200:201] op_sel_hi:[1,0]
	v_pk_mul_f32 v[160:161], v[160:161], v[200:201] op_sel_hi:[1,0]
	v_pk_mul_f32 v[154:155], v[154:155], v[200:201] op_sel_hi:[1,0]
	v_pk_mul_f32 v[156:157], v[156:157], v[200:201] op_sel_hi:[1,0]
	v_pk_mul_f32 v[160:161], v[144:145], v[160:161]
	v_pk_mul_f32 v[158:159], v[142:143], v[158:159]
	v_pk_mul_f32 v[156:157], v[140:141], v[156:157]
	v_pk_mul_f32 v[154:155], v[138:139], v[154:155]
	s_and_saveexec_b64 s[62:63], s[6:7]
	s_cbranch_execz .LBB0_865
	v_mov_b32_e32 v199, v169
	v_lshlrev_b64 v[198:199], 6, v[198:199]
	v_lshl_add_u64 v[198:199], v[174:175], 0, v[198:199]
	global_load_dwordx4 v[214:217], v[198:199], off offset:32
	global_load_dwordx4 v[218:221], v[198:199], off
	s_waitcnt vmcnt(1)
	v_pk_mul_f32 v[198:199], v[156:157], v[216:217]
	v_pk_mul_f32 v[222:223], v[154:155], v[214:215]
	v_pk_mul_f32 v[216:217], v[160:161], v[216:217]
	v_pk_mul_f32 v[214:215], v[158:159], v[214:215]
	s_waitcnt vmcnt(0)
	v_pk_fma_f32 v[160:161], v[160:161], v[220:221], v[198:199] neg_lo:[0,0,1] neg_hi:[0,0,1]
	v_pk_fma_f32 v[158:159], v[158:159], v[218:219], v[222:223] neg_lo:[0,0,1] neg_hi:[0,0,1]
	v_pk_fma_f32 v[156:157], v[156:157], v[220:221], v[216:217]
	v_pk_fma_f32 v[154:155], v[154:155], v[218:219], v[214:215]

;     __device__ __forceinline__ void operator()(const f32x4 (&acc)[2][2][4][2], const Unit& u, int wr, int wc, int fr, int fq) const {
;     ...
;                     int posidx, b, tt; float* cdst = nullptr;
;                     if (!samp) { tt = row & 4095; b = row >> 12; posidx = tt; if (kind >= 1 && tt >= 4096 - W) cdst = out + okp + ((size_t)(b * W + (tt - (4096 - W))) * 4 + wc) * 64; }
;                     else { const int sr = row - 16384; b = sr >> 2; tt = sr & 3; posidx = 4096 + tt; if (kind >= 1) cdst = out + oks + ((size_t)(b * W + (W - 4 + tt)) * 4 + wc) * 64; }
.LBB0_875:
	s_or_b64 exec, exec, s[62:63]
	s_nop 0
	v_add_u32_e32 v196, 0xa0, v180
	s_and_b64 vcc, exec, s[12:13]
	s_mov_b64 s[62:63], -1
	s_cbranch_vccnz .LBB0_877
	v_and_b32_e32 v198, 0xfef, v196
	v_cmp_gt_u32_e32 vcc, s84, v198
	s_or_b64 s[46:47], s[2:3], vcc
	s_lshl_b64 s[62:63], s[54:55], 2
	s_add_u32 s0, s48, s62
	v_add_u32_e32 v148, v213, v198
	s_addc_u32 s68, s49, s63
	s_lshl_b64 s[62:63], s[58:59], 2
	v_ashrrev_i32_e32 v149, 31, v148
	s_add_u32 s62, s0, s62
	v_lshlrev_b64 v[148:149], 10, v[148:149]
	s_addc_u32 s63, s68, s63
	v_lshl_add_u64 v[148:149], s[62:63], 0, v[148:149]
	s_lshl_b32 s0, s74, 2
	v_lshl_add_u64 v[148:149], v[148:149], 0, s[0:1]
	v_cndmask_b32_e64 v195, v149, 0, s[46:47]
	v_cndmask_b32_e64 v194, v148, 0, s[46:47]
	s_mov_b64 s[62:63], 0

;     __device__ __forceinline__ void operator()(const f32x4 (&acc)[2][2][4][2], const Unit& u, int wr, int wc, int fr, int fq) const {
;     ...
;                     const int row = row0 + ai * HALF + m * 16; const float r = __builtin_amdgcn_rsqf(rss[row] * (1.f / 1024.f) + NEPS);
;                     f32x4 v[2][2];
; #pragma unroll
;                     for (int bj = 0; bj < 2; ++bj)
; #pragma unroll
;                         for (int n = 0; n < 2; ++n) v[bj][n] = acc[ai][bj][m][n] * r;
;                     int posidx, b, tt; float* cdst = nullptr;
;                     if (!samp) { tt = row & 4095; b = row >> 12; posidx = tt; if (kind >= 1 && tt >= 4096 - W) cdst = out + okp + ((size_t)(b * W + (tt - (4096 - W))) * 4 + wc) * 64; }
;                     else { const int sr = row - 16384; b = sr >> 2; tt = sr & 3; posidx = 4096 + tt; if (kind >= 1) cdst = out + oks + ((size_t)(b * W + (W - 4 + tt)) * 4 + wc) * 64; }
;                     if (kind < 2) {
;                         float ss = 0.f;
; #pragma unroll
;                         for (int bj = 0; bj < 2; ++bj)
; #pragma unroll
;                             for (int n = 0; n < 2; ++n) ss += (v[bj][n][0] * v[bj][n][0] + v[bj][n][1] * v[bj][n][1]) + (v[bj][n][2] * v[bj][n][2] + v[bj][n][3] * v[bj][n][3]);
;                         ss += __shfl_xor(ss, 16); ss += __shfl_xor(ss, 32);
;                         const float rn = __builtin_amdgcn_rsqf(ss * (1.f / 64.f) + NEPS);
; #pragma unroll
;                         for (int bj = 0; bj < 2; ++bj)
; #pragma unroll
;                             for (int n = 0; n < 2; ++n) v[bj][n] = v[bj][n] * rn * gn[bj][n];
;                         if (fq < 2) {
;                             const f32x4 cs = *(const f32x4*)(rot + (size_t)posidx * 16 + 4 * fq), sn = *(const f32x4*)(rot + (size_t)posidx * 16 + 8 + 4 * fq);
;                             const f32x4 x1 = v[0][0], x2 = v[0][1];
;                             v[0][0] = x1 * cs - x2 * sn; v[0][1] = x2 * cs + x1 * sn;
.LBB0_881:
	s_waitcnt vmcnt(7)
	v_mov_b32_e32 v146, v242
	v_fmamk_f32 v146, v146, 0x3a800000, v210
	v_rsq_f32_e32 v146, v146
	s_and_b64 vcc, exec, s[10:11]
	v_pk_mul_f32 v[160:161], v[32:33], v[146:147] op_sel_hi:[1,0]
	v_pk_mul_f32 v[158:159], v[30:31], v[146:147] op_sel_hi:[1,0]
	v_pk_mul_f32 v[156:157], v[28:29], v[146:147] op_sel_hi:[1,0]
	v_pk_mul_f32 v[154:155], v[26:27], v[146:147] op_sel_hi:[1,0]
	v_pk_mul_f32 v[152:153], v[24:25], v[146:147] op_sel_hi:[1,0]
	v_pk_mul_f32 v[150:151], v[22:23], v[146:147] op_sel_hi:[1,0]
	v_pk_mul_f32 v[148:149], v[20:21], v[146:147] op_sel_hi:[1,0]
	v_pk_mul_f32 v[146:147], v[18:19], v[146:147] op_sel_hi:[1,0]
	s_cbranch_vccnz .LBB0_886
	v_pk_mul_f32 v[200:201], v[160:161], v[160:161]
	v_pk_mul_f32 v[214:215], v[158:159], v[158:159]
	v_and_b32_e32 v187, 64, v211
	v_pk_mov_b32 v[216:217], v[214:215], v[200:201] op_sel:[1,0]
	v_mov_b32_e32 v215, v201
	v_pk_add_f32 v[200:201], v[216:217], v[214:215]
	v_pk_mul_f32 v[214:215], v[156:157], v[156:157]
	v_pk_add_f32 v[200:201], v[200:201], v[200:201] op_sel_hi:[0,1]
	v_pk_mul_f32 v[216:217], v[154:155], v[154:155]
	v_mul_f32_e32 v200, v150, v150
	v_pk_mov_b32 v[218:219], v[216:217], v[214:215] op_sel:[1,0]
	v_mov_b32_e32 v217, v215
	v_pk_add_f32 v[214:215], v[218:219], v[216:217]
	v_pk_fma_f32 v[216:217], v[150:151], v[150:151], v[200:201] op_sel_hi:[1,1,0]
	v_mul_f32_e32 v200, v152, v152
	v_pk_add_f32 v[214:215], v[214:215], v[214:215] op_sel_hi:[0,1]
	v_pk_fma_f32 v[218:219], v[152:153], v[152:153], v[200:201] op_sel_hi:[1,1,0]
	v_mul_f32_e32 v216, v146, v146
	v_mul_f32_e32 v218, v147, v147
	v_mul_f32_e32 v200, v148, v148
	v_mul_f32_e32 v214, v149, v149
	v_xor_b32_e32 v185, 16, v211
	v_add_u32_e32 v187, 64, v187
	v_pk_add_f32 v[216:217], v[216:217], v[218:219]
	v_pk_add_f32 v[200:201], v[200:201], v[214:215]
	v_cmp_lt_i32_e32 vcc, v185, v187
	v_pk_add_f32 v[200:201], v[216:217], v[200:201]
	s_nop 0
	v_cndmask_b32_e32 v185, v211, v185, vcc
	v_add_f32_e32 v183, v200, v201
	v_lshlrev_b32_e32 v185, 2, v185
	ds_bpermute_b32 v185, v185, v183
	s_waitcnt lgkmcnt(0)
	v_add_f32_e32 v183, v183, v185
	v_xor_b32_e32 v185, 32, v211
	v_cmp_lt_i32_e32 vcc, v185, v187
	s_nop 1
	v_cndmask_b32_e32 v185, v211, v185, vcc
	v_lshlrev_b32_e32 v185, 2, v185
	ds_bpermute_b32 v185, v185, v183
	s_waitcnt lgkmcnt(0)
	v_add_f32_e32 v183, v183, v185
	v_fmamk_f32 v183, v183, 0x3c800000, v210
	v_rsq_f32_e32 v200, v183
	s_nop 0
	v_pk_mul_f32 v[158:159], v[158:159], v[200:201] op_sel_hi:[1,0]
	v_pk_mul_f32 v[160:161], v[160:161], v[200:201] op_sel_hi:[1,0]
	v_pk_mul_f32 v[154:155], v[154:155], v[200:201] op_sel_hi:[1,0]
	v_pk_mul_f32 v[156:157], v[156:157], v[200:201] op_sel_hi:[1,0]
	v_pk_mul_f32 v[160:161], v[144:145], v[160:161]
	v_pk_mul_f32 v[158:159], v[142:143], v[158:159]
	v_pk_mul_f32 v[156:157], v[140:141], v[156:157]
	v_pk_mul_f32 v[154:155], v[138:139], v[154:155]
	s_and_saveexec_b64 s[62:63], s[6:7]
	s_cbranch_execz .LBB0_884
	v_mov_b32_e32 v199, v169
	v_lshlrev_b64 v[198:199], 6, v[198:199]
	v_lshl_add_u64 v[198:199], v[174:175], 0, v[198:199]
	global_load_dwordx4 v[214:217], v[198:199], off offset:32
	global_load_dwordx4 v[218:221], v[198:199], off
	s_waitcnt vmcnt(1)
	v_pk_mul_f32 v[198:199], v[156:157], v[216:217]
	v_pk_mul_f32 v[222:223], v[154:155], v[214:215]
	v_pk_mul_f32 v[216:217], v[160:161], v[216:217]
	v_pk_mul_f32 v[214:215], v[158:159], v[214:215]
	s_waitcnt vmcnt(0)
	v_pk_fma_f32 v[160:161], v[160:161], v[220:221], v[198:199] neg_lo:[0,0,1] neg_hi:[0,0,1]
	v_pk_fma_f32 v[158:159], v[158:159], v[218:219], v[222:223] neg_lo:[0,0,1] neg_hi:[0,0,1]
	v_pk_fma_f32 v[156:157], v[156:157], v[220:221], v[216:217]
	v_pk_fma_f32 v[154:155], v[154:155], v[218:219], v[214:215]

;     __device__ __forceinline__ void operator()(const f32x4 (&acc)[2][2][4][2], const Unit& u, int wr, int wc, int fr, int fq) const {
;     ...
;                     int posidx, b, tt; float* cdst = nullptr;
;                     if (!samp) { tt = row & 4095; b = row >> 12; posidx = tt; if (kind >= 1 && tt >= 4096 - W) cdst = out + okp + ((size_t)(b * W + (tt - (4096 - W))) * 4 + wc) * 64; }
;                     else { const int sr = row - 16384; b = sr >> 2; tt = sr & 3; posidx = 4096 + tt; if (kind >= 1) cdst = out + oks + ((size_t)(b * W + (W - 4 + tt)) * 4 + wc) * 64; }
.LBB0_894:
	s_or_b64 exec, exec, s[62:63]
	s_nop 0
	v_add_u32_e32 v194, 0xb0, v180
	s_and_b64 vcc, exec, s[12:13]
	s_mov_b64 s[12:13], -1
	s_cbranch_vccnz .LBB0_896
	v_and_b32_e32 v196, 0xfff, v194
	v_cmp_gt_u32_e32 vcc, s84, v196
	s_or_b64 s[12:13], s[2:3], vcc
	s_lshl_b64 s[46:47], s[54:55], 2
	s_add_u32 s0, s48, s46
	v_add_u32_e32 v148, v213, v196
	s_addc_u32 s54, s49, s47
	s_lshl_b64 s[46:47], s[58:59], 2
	v_ashrrev_i32_e32 v149, 31, v148
	s_add_u32 s46, s0, s46
	v_lshlrev_b64 v[148:149], 10, v[148:149]
	s_addc_u32 s47, s54, s47
	v_lshl_add_u64 v[148:149], s[46:47], 0, v[148:149]
	s_lshl_b32 s0, s74, 2
	v_lshl_add_u64 v[148:149], v[148:149], 0, s[0:1]
	v_cndmask_b32_e64 v189, v149, 0, s[12:13]
	v_cndmask_b32_e64 v188, v148, 0, s[12:13]
	s_mov_b64 s[12:13], 0

;     __device__ __forceinline__ void operator()(const f32x4 (&acc)[2][2][4][2], const Unit& u, int wr, int wc, int fr, int fq) const {
;     ...
;                     const int row = row0 + ai * HALF + m * 16; const float r = __builtin_amdgcn_rsqf(rss[row] * (1.f / 1024.f) + NEPS);
;                     f32x4 v[2][2];
; #pragma unroll
;                     for (int bj = 0; bj < 2; ++bj)
; #pragma unroll
;                         for (int n = 0; n < 2; ++n) v[bj][n] = acc[ai][bj][m][n] * r;
;                     int posidx, b, tt; float* cdst = nullptr;
;                     if (!samp) { tt = row & 4095; b = row >> 12; posidx = tt; if (kind >= 1 && tt >= 4096 - W) cdst = out + okp + ((size_t)(b * W + (tt - (4096 - W))) * 4 + wc) * 64; }
;                     else { const int sr = row - 16384; b = sr >> 2; tt = sr & 3; posidx = 4096 + tt; if (kind >= 1) cdst = out + oks + ((size_t)(b * W + (W - 4 + tt)) * 4 + wc) * 64; }
;                     if (kind < 2) {
;                         float ss = 0.f;
; #pragma unroll
;                         for (int bj = 0; bj < 2; ++bj)
; #pragma unroll
;                             for (int n = 0; n < 2; ++n) ss += (v[bj][n][0] * v[bj][n][0] + v[bj][n][1] * v[bj][n][1]) + (v[bj][n][2] * v[bj][n][2] + v[bj][n][3] * v[bj][n][3]);
;                         ss += __shfl_xor(ss, 16); ss += __shfl_xor(ss, 32);
;                         const float rn = __builtin_amdgcn_rsqf(ss * (1.f / 64.f) + NEPS);
; #pragma unroll
;                         for (int bj = 0; bj < 2; ++bj)
; #pragma unroll
;                             for (int n = 0; n < 2; ++n) v[bj][n] = v[bj][n] * rn * gn[bj][n];
;                         if (fq < 2) {
;                             const f32x4 cs = *(const f32x4*)(rot + (size_t)posidx * 16 + 4 * fq), sn = *(const f32x4*)(rot + (size_t)posidx * 16 + 8 + 4 * fq);
;                             const f32x4 x1 = v[0][0], x2 = v[0][1];
;                             v[0][0] = x1 * cs - x2 * sn; v[0][1] = x2 * cs + x1 * sn;
.LBB0_900:
	s_waitcnt vmcnt(7)
	v_mov_b32_e32 v146, v243
	v_fmamk_f32 v146, v146, 0x3a800000, v210
	v_rsq_f32_e32 v146, v146
	s_and_b64 vcc, exec, s[10:11]
	v_pk_mul_f32 v[160:161], v[16:17], v[146:147] op_sel_hi:[1,0]
	v_pk_mul_f32 v[158:159], v[14:15], v[146:147] op_sel_hi:[1,0]
	v_pk_mul_f32 v[156:157], v[12:13], v[146:147] op_sel_hi:[1,0]
	v_pk_mul_f32 v[154:155], v[10:11], v[146:147] op_sel_hi:[1,0]
	v_pk_mul_f32 v[152:153], v[8:9], v[146:147] op_sel_hi:[1,0]
	v_pk_mul_f32 v[150:151], v[6:7], v[146:147] op_sel_hi:[1,0]
	v_pk_mul_f32 v[148:149], v[4:5], v[146:147] op_sel_hi:[1,0]
	v_pk_mul_f32 v[146:147], v[2:3], v[146:147] op_sel_hi:[1,0]
	s_cbranch_vccnz .LBB0_905
	v_pk_mul_f32 v[198:199], v[160:161], v[160:161]
	v_pk_mul_f32 v[200:201], v[158:159], v[158:159]
	v_and_b32_e32 v185, 64, v211
	v_pk_mov_b32 v[214:215], v[200:201], v[198:199] op_sel:[1,0]
	v_mov_b32_e32 v201, v199
	v_pk_add_f32 v[198:199], v[214:215], v[200:201]
	v_pk_mul_f32 v[200:201], v[156:157], v[156:157]
	v_pk_add_f32 v[198:199], v[198:199], v[198:199] op_sel_hi:[0,1]
	v_pk_mul_f32 v[214:215], v[154:155], v[154:155]
	v_mul_f32_e32 v198, v150, v150
	v_pk_mov_b32 v[216:217], v[214:215], v[200:201] op_sel:[1,0]
	v_mov_b32_e32 v215, v201
	v_pk_add_f32 v[200:201], v[216:217], v[214:215]
	v_pk_fma_f32 v[214:215], v[150:151], v[150:151], v[198:199] op_sel_hi:[1,1,0]
	v_mul_f32_e32 v198, v152, v152
	v_pk_add_f32 v[200:201], v[200:201], v[200:201] op_sel_hi:[0,1]
	v_pk_fma_f32 v[216:217], v[152:153], v[152:153], v[198:199] op_sel_hi:[1,1,0]
	v_mul_f32_e32 v214, v146, v146
	v_mul_f32_e32 v216, v147, v147
	v_mul_f32_e32 v198, v148, v148
	v_mul_f32_e32 v200, v149, v149
	v_xor_b32_e32 v183, 16, v211
	v_add_u32_e32 v185, 64, v185
	v_pk_add_f32 v[214:215], v[214:215], v[216:217]
	v_pk_add_f32 v[198:199], v[198:199], v[200:201]
	v_cmp_lt_i32_e32 vcc, v183, v185
	v_pk_add_f32 v[198:199], v[214:215], v[198:199]
	s_nop 0
	v_cndmask_b32_e32 v183, v211, v183, vcc
	v_add_f32_e32 v181, v198, v199
	v_lshlrev_b32_e32 v183, 2, v183
	ds_bpermute_b32 v183, v183, v181
	s_waitcnt lgkmcnt(0)
	v_add_f32_e32 v181, v181, v183
	v_xor_b32_e32 v183, 32, v211
	v_cmp_lt_i32_e32 vcc, v183, v185
	s_nop 1
	v_cndmask_b32_e32 v183, v211, v183, vcc
	v_lshlrev_b32_e32 v183, 2, v183
	ds_bpermute_b32 v183, v183, v181
	s_waitcnt lgkmcnt(0)
	v_add_f32_e32 v181, v181, v183
	v_fmamk_f32 v181, v181, 0x3c800000, v210
	v_rsq_f32_e32 v198, v181
	s_nop 0
	v_pk_mul_f32 v[158:159], v[158:159], v[198:199] op_sel_hi:[1,0]
	v_pk_mul_f32 v[160:161], v[160:161], v[198:199] op_sel_hi:[1,0]
	v_pk_mul_f32 v[158:159], v[142:143], v[158:159]
	v_pk_mul_f32 v[160:161], v[144:145], v[160:161]
	v_pk_mul_f32 v[142:143], v[154:155], v[198:199] op_sel_hi:[1,0]
	v_pk_mul_f32 v[144:145], v[156:157], v[198:199] op_sel_hi:[1,0]
	v_pk_mul_f32 v[154:155], v[138:139], v[142:143]
	v_pk_mul_f32 v[156:157], v[140:141], v[144:145]
	s_and_saveexec_b64 s[4:5], s[6:7]
	s_cbranch_execz .LBB0_903
	v_mov_b32_e32 v197, v169
	v_lshlrev_b64 v[138:139], 6, v[196:197]
	v_lshl_add_u64 v[142:143], v[174:175], 0, v[138:139]
	global_load_dwordx4 v[138:141], v[142:143], off offset:32
	s_nop 0
	global_load_dwordx4 v[142:145], v[142:143], off
	s_waitcnt vmcnt(1)
	v_pk_mul_f32 v[196:197], v[156:157], v[140:141]
	v_pk_mul_f32 v[200:201], v[154:155], v[138:139]
	v_pk_mul_f32 v[140:141], v[160:161], v[140:141]
	v_pk_mul_f32 v[138:139], v[158:159], v[138:139]
	s_waitcnt vmcnt(0)
	v_pk_fma_f32 v[160:161], v[160:161], v[144:145], v[196:197] neg_lo:[0,0,1] neg_hi:[0,0,1]
	v_pk_fma_f32 v[158:159], v[158:159], v[142:143], v[200:201] neg_lo:[0,0,1] neg_hi:[0,0,1]
	v_pk_fma_f32 v[156:157], v[156:157], v[144:145], v[140:141]
	v_pk_fma_f32 v[154:155], v[154:155], v[142:143], v[138:139]

; __device__ __forceinline__ unsigned cvt_pk_bf16(float lo, float hi) { unsigned r; asm volatile("v_cvt_pk_bf16_f32 %0, %1, %2" : "=v"(r) : "v"(lo), "v"(hi)); return r; }
; __device__ __forceinline__ float sigmoid_f(float x) { return __builtin_amdgcn_rcpf(1.f + __builtin_amdgcn_exp2f(-1.4426950408889634f * x)); }
;     __device__ __forceinline__ void operator()(const f32x4 (&acc)[2][2][4][2], const Unit& u, int wr, int wc, int fr, int fq) const {
;     ...
;         if (pn < 4) {
;             const int col0 = pn * 128 + wc * 32 + 8 * fq;
; #pragma unroll
;             for (int ai = 0; ai < 2; ++ai)
; #pragma unroll
;                 for (int m = 0; m < 4; ++m) {
;                     const int row = row0 + ai * HALF + m * 16; const float r = __builtin_amdgcn_rsqf(rss[row] * (1.f / 1024.f) + NEPS);
;                     float o[8];
; #pragma unroll
;                     for (int n = 0; n < 2; ++n)
; #pragma unroll
;                         for (int e = 0; e < 4; ++e) o[4 * n + e] = (acc[ai][0][m][n][e] * r) * sigmoid_f(acc[ai][1][m][n][e] * r);
;                     u32x4 w; w.x = cvt_pk_bf16(o[0], o[1]); w.y = cvt_pk_bf16(o[2], o[3]); w.z = cvt_pk_bf16(o[4], o[5]); w.w = cvt_pk_bf16(o[6], o[7]);
;                     *(u32x4*)(U + (size_t)row * 512 + col0) = w;
;                     float* cp = nullptr;
;                     if (!samp) { const int t = row & 4095, b = row >> 12; if (t >= 4066) cp = out + 22806528 + ((size_t)(b * 30 + (t - 4066))) * 512 + col0; }
;                     else { const int sr = row - 16384; cp = out + 199028736 + ((size_t)((sr >> 2) * 30 + 26 + (sr & 3))) * 512 + col0; }
;                     if (cp) { *(f32x4*)cp = (f32x4){o[0], o[1], o[2], o[3]}; *(f32x4*)(cp + 4) = (f32x4){o[4], o[5], o[6], o[7]}; }
.LBB0_917:
	v_ashrrev_i32_e32 v181, 31, v180
	v_lshl_add_u64 v[132:133], v[180:181], 2, s[40:41]
	global_load_dword v236, v[132:133], off
	global_load_dword v237, v[132:133], off offset:64
	global_load_dword v238, v[132:133], off offset:128
	global_load_dword v239, v[132:133], off offset:192
	global_load_dword v240, v[132:133], off offset:512
	global_load_dword v241, v[132:133], off offset:576
	global_load_dword v242, v[132:133], off offset:640
	global_load_dword v243, v[132:133], off offset:704
	v_cndmask_b32_e64 v137, 0, 1, s[52:53]
	v_cmp_ne_u32_e64 s[10:11], 1, v137
	v_readlane_b32 s2, v250, 10
	v_lshl_or_b32 v130, s38, 7, v173
	v_lshlrev_b64 v[134:135], 10, v[180:181]
	v_readlane_b32 s3, v250, 11
	v_ashrrev_i32_e32 v131, 31, v130
	s_andn2_b64 vcc, exec, s[52:53]
	v_lshl_add_u64 v[134:135], s[2:3], 0, v[134:135]
	v_lshl_add_u64 v[134:135], v[130:131], 1, v[134:135]
	s_waitcnt vmcnt(0)
	v_mov_b32_e32 v136, v236
	v_fmamk_f32 v136, v136, 0x3a800000, v210
	v_rsq_f32_e32 v136, v136
	s_nop 0
	v_mul_f32_e32 v137, v118, v136
	v_mul_f32_e32 v138, v119, v136
	v_pk_mul_f32 v[118:119], v[126:127], v[136:137] op_sel_hi:[1,0]
	v_mul_f32_e32 v126, v120, v136
	v_mul_f32_e32 v127, v121, v136
	v_pk_mul_f32 v[120:121], v[128:129], v[136:137] op_sel_hi:[1,0]
	v_mul_f32_e32 v128, v114, v136
	v_mul_f32_e32 v129, v115, v136
	v_pk_mul_f32 v[114:115], v[122:123], v[136:137] op_sel_hi:[1,0]
	v_mul_f32_e32 v122, v116, v136
	v_mul_f32_e32 v123, v117, v136
	v_pk_mul_f32 v[116:117], v[124:125], v[136:137] op_sel_hi:[1,0]
	v_mul_f32_e32 v124, 0xbfb8aa3b, v137
	v_mul_f32_e32 v125, 0xbfb8aa3b, v138
	v_mul_f32_e32 v126, 0xbfb8aa3b, v126
	v_mul_f32_e32 v127, 0xbfb8aa3b, v127
	v_mul_f32_e32 v128, 0xbfb8aa3b, v128
	v_mul_f32_e32 v129, 0xbfb8aa3b, v129
	v_mul_f32_e32 v122, 0xbfb8aa3b, v122
	v_mul_f32_e32 v123, 0xbfb8aa3b, v123
	v_exp_f32_e32 v124, v124
	v_exp_f32_e32 v125, v125
	v_exp_f32_e32 v126, v126
	v_exp_f32_e32 v127, v127
	v_exp_f32_e32 v128, v128
	v_exp_f32_e32 v129, v129
	v_exp_f32_e32 v122, v122
	v_exp_f32_e32 v123, v123
	v_add_f32_e32 v124, 1.0, v124
	v_add_f32_e32 v125, 1.0, v125
	v_add_f32_e32 v126, 1.0, v126
	v_add_f32_e32 v127, 1.0, v127
	v_add_f32_e32 v128, 1.0, v128
	v_add_f32_e32 v129, 1.0, v129
	v_add_f32_e32 v136, 1.0, v122
	v_add_f32_e32 v137, 1.0, v123
	v_rcp_f32_e32 v122, v124
	v_rcp_f32_e32 v123, v125
	v_rcp_f32_e32 v124, v126
	v_rcp_f32_e32 v125, v127
	v_rcp_f32_e32 v126, v128
	v_rcp_f32_e32 v127, v129
	v_rcp_f32_e32 v128, v136
	v_rcp_f32_e32 v129, v137
	v_pk_mul_f32 v[118:119], v[118:119], v[122:123]
	v_pk_mul_f32 v[120:121], v[120:121], v[124:125]
	v_cvt_pk_bf16_f32 v122, v118, v119
	v_pk_mul_f32 v[114:115], v[114:115], v[126:127]
	v_cvt_pk_bf16_f32 v123, v120, v121
	v_pk_mul_f32 v[116:117], v[116:117], v[128:129]
	v_cvt_pk_bf16_f32 v124, v114, v115
	s_nop 0
	v_cvt_pk_bf16_f32 v125, v116, v117
	global_store_dwordx4 v[134:135], v[122:125], off
	s_nop 1
	v_mov_b64_e32 v[122:123], 0
	s_cbranch_vccnz .LBB0_919
	v_add_u32_e32 v122, 0xffffc000, v180
	v_ashrrev_i32_e32 v122, 2, v122
	v_mad_u64_u32 v[122:123], s[2:3], v122, 30, v[172:173]
	v_ashrrev_i32_e32 v123, 31, v122
	v_lshlrev_b64 v[122:123], 11, v[122:123]
	v_lshl_add_u64 v[122:123], s[20:21], 0, v[122:123]
	v_lshl_add_u64 v[122:123], v[130:131], 2, v[122:123]

; __device__ __forceinline__ unsigned cvt_pk_bf16(float lo, float hi) { unsigned r; asm volatile("v_cvt_pk_bf16_f32 %0, %1, %2" : "=v"(r) : "v"(lo), "v"(hi)); return r; }
; __device__ __forceinline__ float sigmoid_f(float x) { return __builtin_amdgcn_rcpf(1.f + __builtin_amdgcn_exp2f(-1.4426950408889634f * x)); }
;     __device__ __forceinline__ void operator()(const f32x4 (&acc)[2][2][4][2], const Unit& u, int wr, int wc, int fr, int fq) const {
;     ...
;                     const int row = row0 + ai * HALF + m * 16; const float r = __builtin_amdgcn_rsqf(rss[row] * (1.f / 1024.f) + NEPS);
;                     float o[8];
; #pragma unroll
;                     for (int n = 0; n < 2; ++n)
; #pragma unroll
;                         for (int e = 0; e < 4; ++e) o[4 * n + e] = (acc[ai][0][m][n][e] * r) * sigmoid_f(acc[ai][1][m][n][e] * r);
;                     u32x4 w; w.x = cvt_pk_bf16(o[0], o[1]); w.y = cvt_pk_bf16(o[2], o[3]); w.z = cvt_pk_bf16(o[4], o[5]); w.w = cvt_pk_bf16(o[6], o[7]);
;                     *(u32x4*)(U + (size_t)row * 512 + col0) = w;
;                     float* cp = nullptr;
;                     if (!samp) { const int t = row & 4095, b = row >> 12; if (t >= 4066) cp = out + 22806528 + ((size_t)(b * 30 + (t - 4066))) * 512 + col0; }
;                     else { const int sr = row - 16384; cp = out + 199028736 + ((size_t)((sr >> 2) * 30 + 26 + (sr & 3))) * 512 + col0; }
.LBB0_921:
	s_or_b64 exec, exec, s[2:3]
	s_nop 0
	v_or_b32_e32 v114, 16, v180
	v_ashrrev_i32_e32 v115, 31, v114
	v_lshl_add_u64 v[116:117], v[114:115], 2, s[40:41]
	s_nop 0
	v_readlane_b32 s2, v250, 10
	v_lshlrev_b64 v[114:115], 10, v[114:115]
	v_readlane_b32 s3, v250, 11
	s_and_b64 vcc, exec, s[10:11]
	s_waitcnt vmcnt(7)
	v_mov_b32_e32 v116, v237
	v_fmamk_f32 v116, v116, 0x3a800000, v210
	v_rsq_f32_e32 v116, v116
	v_lshl_add_u64 v[114:115], s[2:3], 0, v[114:115]
	v_lshl_add_u64 v[114:115], v[130:131], 1, v[114:115]
	v_mul_f32_e32 v117, v102, v116
	v_mul_f32_e32 v118, v103, v116
	v_pk_mul_f32 v[102:103], v[110:111], v[116:117] op_sel_hi:[1,0]
	v_mul_f32_e32 v110, v104, v116
	v_mul_f32_e32 v111, v105, v116
	v_pk_mul_f32 v[104:105], v[112:113], v[116:117] op_sel_hi:[1,0]
	v_mul_f32_e32 v112, v98, v116
	v_mul_f32_e32 v113, v99, v116
	v_pk_mul_f32 v[98:99], v[106:107], v[116:117] op_sel_hi:[1,0]
	v_mul_f32_e32 v106, v100, v116
	v_mul_f32_e32 v107, v101, v116
	v_pk_mul_f32 v[100:101], v[108:109], v[116:117] op_sel_hi:[1,0]
	v_mul_f32_e32 v108, 0xbfb8aa3b, v117
	v_mul_f32_e32 v109, 0xbfb8aa3b, v118
	v_mul_f32_e32 v110, 0xbfb8aa3b, v110
	v_mul_f32_e32 v111, 0xbfb8aa3b, v111
	v_mul_f32_e32 v112, 0xbfb8aa3b, v112
	v_mul_f32_e32 v113, 0xbfb8aa3b, v113
	v_mul_f32_e32 v106, 0xbfb8aa3b, v106
	v_mul_f32_e32 v107, 0xbfb8aa3b, v107
	v_exp_f32_e32 v108, v108
	v_exp_f32_e32 v109, v109
	v_exp_f32_e32 v110, v110
	v_exp_f32_e32 v111, v111
	v_exp_f32_e32 v112, v112
	v_exp_f32_e32 v113, v113
	v_exp_f32_e32 v106, v106
	v_exp_f32_e32 v107, v107
	v_add_f32_e32 v108, 1.0, v108
	v_add_f32_e32 v109, 1.0, v109
	v_add_f32_e32 v110, 1.0, v110
	v_add_f32_e32 v111, 1.0, v111
	v_add_f32_e32 v112, 1.0, v112
	v_add_f32_e32 v113, 1.0, v113
	v_add_f32_e32 v116, 1.0, v106
	v_add_f32_e32 v117, 1.0, v107
	v_rcp_f32_e32 v106, v108
	v_rcp_f32_e32 v107, v109
	v_rcp_f32_e32 v108, v110
	v_rcp_f32_e32 v109, v111
	v_rcp_f32_e32 v110, v112
	v_rcp_f32_e32 v111, v113
	v_rcp_f32_e32 v112, v116
	v_rcp_f32_e32 v113, v117
	v_pk_mul_f32 v[102:103], v[102:103], v[106:107]
	v_pk_mul_f32 v[104:105], v[104:105], v[108:109]
	v_cvt_pk_bf16_f32 v106, v102, v103
	v_pk_mul_f32 v[98:99], v[98:99], v[110:111]
	v_cvt_pk_bf16_f32 v107, v104, v105
	v_pk_mul_f32 v[100:101], v[100:101], v[112:113]
	v_cvt_pk_bf16_f32 v108, v98, v99
	s_nop 0
	v_cvt_pk_bf16_f32 v109, v100, v101
	global_store_dwordx4 v[114:115], v[106:109], off
	s_nop 1
	v_mov_b64_e32 v[106:107], 0
	s_cbranch_vccnz .LBB0_923
	v_add_u32_e32 v106, 0xffffc010, v180
	v_ashrrev_i32_e32 v106, 2, v106
	v_mad_u64_u32 v[106:107], s[2:3], v106, 30, v[172:173]
	v_ashrrev_i32_e32 v107, 31, v106
	v_lshlrev_b64 v[106:107], 11, v[106:107]
	v_lshl_add_u64 v[106:107], s[20:21], 0, v[106:107]
	v_lshl_add_u64 v[106:107], v[130:131], 2, v[106:107]

; __device__ __forceinline__ unsigned cvt_pk_bf16(float lo, float hi) { unsigned r; asm volatile("v_cvt_pk_bf16_f32 %0, %1, %2" : "=v"(r) : "v"(lo), "v"(hi)); return r; }
; __device__ __forceinline__ float sigmoid_f(float x) { return __builtin_amdgcn_rcpf(1.f + __builtin_amdgcn_exp2f(-1.4426950408889634f * x)); }
;     __device__ __forceinline__ void operator()(const f32x4 (&acc)[2][2][4][2], const Unit& u, int wr, int wc, int fr, int fq) const {
;     ...
;                     const int row = row0 + ai * HALF + m * 16; const float r = __builtin_amdgcn_rsqf(rss[row] * (1.f / 1024.f) + NEPS);
;                     float o[8];
; #pragma unroll
;                     for (int n = 0; n < 2; ++n)
; #pragma unroll
;                         for (int e = 0; e < 4; ++e) o[4 * n + e] = (acc[ai][0][m][n][e] * r) * sigmoid_f(acc[ai][1][m][n][e] * r);
;                     u32x4 w; w.x = cvt_pk_bf16(o[0], o[1]); w.y = cvt_pk_bf16(o[2], o[3]); w.z = cvt_pk_bf16(o[4], o[5]); w.w = cvt_pk_bf16(o[6], o[7]);
;                     *(u32x4*)(U + (size_t)row * 512 + col0) = w;
;                     float* cp = nullptr;
;                     if (!samp) { const int t = row & 4095, b = row >> 12; if (t >= 4066) cp = out + 22806528 + ((size_t)(b * 30 + (t - 4066))) * 512 + col0; }
;                     else { const int sr = row - 16384; cp = out + 199028736 + ((size_t)((sr >> 2) * 30 + 26 + (sr & 3))) * 512 + col0; }
.LBB0_925:
	s_or_b64 exec, exec, s[2:3]
	s_nop 0
	v_or_b32_e32 v98, 32, v180
	v_ashrrev_i32_e32 v99, 31, v98
	v_lshl_add_u64 v[100:101], v[98:99], 2, s[40:41]
	s_nop 0
	v_cndmask_b32_e64 v100, 0, 1, s[50:51]
	v_cmp_ne_u32_e64 s[8:9], 1, v100
	v_lshlrev_b64 v[100:101], 10, v[98:99]
	v_readlane_b32 s2, v250, 10
	s_ashr_i32 s0, s27, 12
	v_readlane_b32 s3, v250, 11
	s_mul_i32 s0, s0, 30
	s_addk_i32 s0, 0xf01e
	v_lshl_add_u64 v[100:101], s[2:3], 0, v[100:101]
	s_andn2_b64 vcc, exec, s[50:51]
	v_lshl_add_u64 v[100:101], v[130:131], 1, v[100:101]
	s_mov_b64 s[2:3], -1
	s_waitcnt vmcnt(7)
	v_mov_b32_e32 v102, v238
	v_fmamk_f32 v99, v102, 0x3a800000, v210
	v_rsq_f32_e32 v102, v99
	s_nop 0
	v_mul_f32_e32 v103, v87, v102
	v_mul_f32_e32 v99, v86, v102
	v_pk_mul_f32 v[86:87], v[94:95], v[102:103] op_sel_hi:[1,0]
	v_mul_f32_e32 v94, v88, v102
	v_mul_f32_e32 v95, v89, v102
	v_pk_mul_f32 v[88:89], v[96:97], v[102:103] op_sel_hi:[1,0]
	v_mul_f32_e32 v96, v82, v102
	v_mul_f32_e32 v97, v83, v102
	v_pk_mul_f32 v[82:83], v[90:91], v[102:103] op_sel_hi:[1,0]
	v_mul_f32_e32 v90, v84, v102
	v_mul_f32_e32 v91, v85, v102
	v_pk_mul_f32 v[84:85], v[92:93], v[102:103] op_sel_hi:[1,0]
	v_mul_f32_e32 v92, 0xbfb8aa3b, v99
	v_mul_f32_e32 v93, 0xbfb8aa3b, v103
	v_mul_f32_e32 v94, 0xbfb8aa3b, v94
	v_mul_f32_e32 v95, 0xbfb8aa3b, v95
	v_mul_f32_e32 v96, 0xbfb8aa3b, v96
	v_mul_f32_e32 v97, 0xbfb8aa3b, v97
	v_mul_f32_e32 v90, 0xbfb8aa3b, v90
	v_mul_f32_e32 v91, 0xbfb8aa3b, v91
	v_exp_f32_e32 v92, v92
	v_exp_f32_e32 v93, v93
	v_exp_f32_e32 v94, v94
	v_exp_f32_e32 v95, v95
	v_exp_f32_e32 v96, v96
	v_exp_f32_e32 v97, v97
	v_exp_f32_e32 v90, v90
	v_exp_f32_e32 v91, v91
	v_add_f32_e32 v92, 1.0, v92
	v_add_f32_e32 v93, 1.0, v93
	v_add_f32_e32 v94, 1.0, v94
	v_add_f32_e32 v95, 1.0, v95
	v_add_f32_e32 v96, 1.0, v96
	v_add_f32_e32 v97, 1.0, v97
	v_add_f32_e32 v99, 1.0, v90
	v_add_f32_e32 v102, 1.0, v91
	v_rcp_f32_e32 v90, v92
	v_rcp_f32_e32 v91, v93
	v_rcp_f32_e32 v92, v94
	v_rcp_f32_e32 v93, v95
	v_rcp_f32_e32 v94, v96
	v_rcp_f32_e32 v95, v97
	v_rcp_f32_e32 v96, v99
	v_rcp_f32_e32 v97, v102
	v_pk_mul_f32 v[86:87], v[86:87], v[90:91]
	v_pk_mul_f32 v[88:89], v[88:89], v[92:93]
	v_pk_mul_f32 v[82:83], v[82:83], v[94:95]
	v_pk_mul_f32 v[84:85], v[84:85], v[96:97]
	v_cvt_pk_bf16_f32 v90, v86, v87
	v_cvt_pk_bf16_f32 v91, v88, v89
	v_cvt_pk_bf16_f32 v92, v82, v83
	s_nop 0
	v_cvt_pk_bf16_f32 v93, v84, v85
	global_store_dwordx4 v[100:101], v[90:93], off
	s_cbranch_vccnz .LBB0_952
	s_nop 0
	v_and_b32_e32 v92, 0xfef, v98
	v_add_u32_e32 v90, s0, v92
	v_ashrrev_i32_e32 v91, 31, v90
	v_lshlrev_b64 v[90:91], 11, v[90:91]
	v_lshl_add_u64 v[90:91], s[22:23], 0, v[90:91]
	v_lshl_add_u64 v[90:91], v[130:131], 2, v[90:91]
	v_cmp_lt_u32_e32 vcc, s78, v92
	s_nop 1
	v_cndmask_b32_e32 v91, 0, v91, vcc
	v_cndmask_b32_e32 v90, 0, v90, vcc
	s_cbranch_execz .LBB0_953

; __device__ __forceinline__ unsigned cvt_pk_bf16(float lo, float hi) { unsigned r; asm volatile("v_cvt_pk_bf16_f32 %0, %1, %2" : "=v"(r) : "v"(lo), "v"(hi)); return r; }
; __device__ __forceinline__ float sigmoid_f(float x) { return __builtin_amdgcn_rcpf(1.f + __builtin_amdgcn_exp2f(-1.4426950408889634f * x)); }
;     __device__ __forceinline__ void operator()(const f32x4 (&acc)[2][2][4][2], const Unit& u, int wr, int wc, int fr, int fq) const {
;     ...
;                     const int row = row0 + ai * HALF + m * 16; const float r = __builtin_amdgcn_rsqf(rss[row] * (1.f / 1024.f) + NEPS);
;                     float o[8];
; #pragma unroll
;                     for (int n = 0; n < 2; ++n)
; #pragma unroll
;                         for (int e = 0; e < 4; ++e) o[4 * n + e] = (acc[ai][0][m][n][e] * r) * sigmoid_f(acc[ai][1][m][n][e] * r);
;                     u32x4 w; w.x = cvt_pk_bf16(o[0], o[1]); w.y = cvt_pk_bf16(o[2], o[3]); w.z = cvt_pk_bf16(o[4], o[5]); w.w = cvt_pk_bf16(o[6], o[7]);
;                     *(u32x4*)(U + (size_t)row * 512 + col0) = w;
;                     float* cp = nullptr;
;                     if (!samp) { const int t = row & 4095, b = row >> 12; if (t >= 4066) cp = out + 22806528 + ((size_t)(b * 30 + (t - 4066))) * 512 + col0; }
;                     else { const int sr = row - 16384; cp = out + 199028736 + ((size_t)((sr >> 2) * 30 + 26 + (sr & 3))) * 512 + col0; }
.LBB0_929:
	s_or_b64 exec, exec, s[2:3]
	s_nop 0
	v_or_b32_e32 v82, 48, v180
	v_ashrrev_i32_e32 v83, 31, v82
	v_lshl_add_u64 v[84:85], v[82:83], 2, s[40:41]
	s_nop 0
	v_lshlrev_b64 v[86:87], 10, v[82:83]
	v_readlane_b32 s2, v250, 10
	v_readlane_b32 s3, v250, 11
	s_and_b64 vcc, exec, s[8:9]
	s_waitcnt vmcnt(7)
	v_mov_b32_e32 v84, v239
	v_fmamk_f32 v84, v84, 0x3a800000, v210
	v_rsq_f32_e32 v84, v84
	v_lshl_add_u64 v[86:87], s[2:3], 0, v[86:87]
	v_lshl_add_u64 v[86:87], v[130:131], 1, v[86:87]
	s_mov_b64 s[2:3], -1
	v_mul_f32_e32 v85, v71, v84
	v_mul_f32_e32 v83, v70, v84
	v_pk_mul_f32 v[70:71], v[78:79], v[84:85] op_sel_hi:[1,0]
	v_mul_f32_e32 v78, v72, v84
	v_mul_f32_e32 v79, v73, v84
	v_pk_mul_f32 v[72:73], v[80:81], v[84:85] op_sel_hi:[1,0]
	v_mul_f32_e32 v80, v66, v84
	v_mul_f32_e32 v81, v67, v84
	v_pk_mul_f32 v[66:67], v[74:75], v[84:85] op_sel_hi:[1,0]
	v_mul_f32_e32 v74, v68, v84
	v_mul_f32_e32 v75, v69, v84
	v_pk_mul_f32 v[68:69], v[76:77], v[84:85] op_sel_hi:[1,0]
	v_mul_f32_e32 v76, 0xbfb8aa3b, v83
	v_mul_f32_e32 v77, 0xbfb8aa3b, v85
	v_mul_f32_e32 v78, 0xbfb8aa3b, v78
	v_mul_f32_e32 v79, 0xbfb8aa3b, v79
	v_mul_f32_e32 v80, 0xbfb8aa3b, v80
	v_mul_f32_e32 v81, 0xbfb8aa3b, v81
	v_mul_f32_e32 v74, 0xbfb8aa3b, v74
	v_mul_f32_e32 v75, 0xbfb8aa3b, v75
	v_exp_f32_e32 v76, v76
	v_exp_f32_e32 v77, v77
	v_exp_f32_e32 v78, v78
	v_exp_f32_e32 v79, v79
	v_exp_f32_e32 v80, v80
	v_exp_f32_e32 v81, v81
	v_exp_f32_e32 v74, v74
	v_exp_f32_e32 v75, v75
	v_add_f32_e32 v76, 1.0, v76
	v_add_f32_e32 v77, 1.0, v77
	v_add_f32_e32 v78, 1.0, v78
	v_add_f32_e32 v79, 1.0, v79
	v_add_f32_e32 v80, 1.0, v80
	v_add_f32_e32 v81, 1.0, v81
	v_add_f32_e32 v83, 1.0, v74
	v_add_f32_e32 v84, 1.0, v75
	v_rcp_f32_e32 v74, v76
	v_rcp_f32_e32 v75, v77
	v_rcp_f32_e32 v76, v78
	v_rcp_f32_e32 v77, v79
	v_rcp_f32_e32 v78, v80
	v_rcp_f32_e32 v79, v81
	v_rcp_f32_e32 v80, v83
	v_rcp_f32_e32 v81, v84
	v_pk_mul_f32 v[70:71], v[70:71], v[74:75]
	v_pk_mul_f32 v[72:73], v[72:73], v[76:77]
	v_pk_mul_f32 v[66:67], v[66:67], v[78:79]
	v_pk_mul_f32 v[68:69], v[68:69], v[80:81]
	v_cvt_pk_bf16_f32 v74, v70, v71
	v_cvt_pk_bf16_f32 v75, v72, v73
	v_cvt_pk_bf16_f32 v76, v66, v67
	s_nop 0
	v_cvt_pk_bf16_f32 v77, v68, v69
	global_store_dwordx4 v[86:87], v[74:77], off
	s_cbranch_vccnz .LBB0_954
	s_nop 0
	v_and_b32_e32 v76, 0xfff, v82
	v_add_u32_e32 v74, s0, v76
	v_ashrrev_i32_e32 v75, 31, v74
	v_lshlrev_b64 v[74:75], 11, v[74:75]
	v_lshl_add_u64 v[74:75], s[22:23], 0, v[74:75]
	v_lshl_add_u64 v[74:75], v[130:131], 2, v[74:75]
	v_cmp_lt_u32_e32 vcc, s78, v76
	s_nop 1
	v_cndmask_b32_e32 v75, 0, v75, vcc
	v_cndmask_b32_e32 v74, 0, v74, vcc
	s_cbranch_execz .LBB0_955

; __device__ __forceinline__ unsigned cvt_pk_bf16(float lo, float hi) { unsigned r; asm volatile("v_cvt_pk_bf16_f32 %0, %1, %2" : "=v"(r) : "v"(lo), "v"(hi)); return r; }
; __device__ __forceinline__ float sigmoid_f(float x) { return __builtin_amdgcn_rcpf(1.f + __builtin_amdgcn_exp2f(-1.4426950408889634f * x)); }
;     __device__ __forceinline__ void operator()(const f32x4 (&acc)[2][2][4][2], const Unit& u, int wr, int wc, int fr, int fq) const {
;     ...
;                     const int row = row0 + ai * HALF + m * 16; const float r = __builtin_amdgcn_rsqf(rss[row] * (1.f / 1024.f) + NEPS);
;                     float o[8];
; #pragma unroll
;                     for (int n = 0; n < 2; ++n)
; #pragma unroll
;                         for (int e = 0; e < 4; ++e) o[4 * n + e] = (acc[ai][0][m][n][e] * r) * sigmoid_f(acc[ai][1][m][n][e] * r);
;                     u32x4 w; w.x = cvt_pk_bf16(o[0], o[1]); w.y = cvt_pk_bf16(o[2], o[3]); w.z = cvt_pk_bf16(o[4], o[5]); w.w = cvt_pk_bf16(o[6], o[7]);
;                     *(u32x4*)(U + (size_t)row * 512 + col0) = w;
;                     float* cp = nullptr;
;                     if (!samp) { const int t = row & 4095, b = row >> 12; if (t >= 4066) cp = out + 22806528 + ((size_t)(b * 30 + (t - 4066))) * 512 + col0; }
;                     else { const int sr = row - 16384; cp = out + 199028736 + ((size_t)((sr >> 2) * 30 + 26 + (sr & 3))) * 512 + col0; }
.LBB0_933:
	s_or_b64 exec, exec, s[2:3]
	s_nop 0
	v_add_u32_e32 v66, 0x80, v180
	v_ashrrev_i32_e32 v67, 31, v66
	v_lshlrev_b64 v[70:71], 10, v[66:67]
	v_readlane_b32 s2, v250, 10
	v_readlane_b32 s3, v250, 11
	s_and_b64 vcc, exec, s[10:11]
	s_waitcnt vmcnt(7)
	v_mov_b32_e32 v68, v240
	v_fmamk_f32 v68, v68, 0x3a800000, v210
	v_rsq_f32_e32 v68, v68
	v_lshl_add_u64 v[70:71], s[2:3], 0, v[70:71]
	v_lshl_add_u64 v[70:71], v[130:131], 1, v[70:71]
	v_mul_f32_e32 v69, v55, v68
	v_mul_f32_e32 v67, v54, v68
	v_pk_mul_f32 v[54:55], v[62:63], v[68:69] op_sel_hi:[1,0]
	v_mul_f32_e32 v62, v56, v68
	v_mul_f32_e32 v63, v57, v68
	v_pk_mul_f32 v[56:57], v[64:65], v[68:69] op_sel_hi:[1,0]
	v_mul_f32_e32 v64, v50, v68
	v_mul_f32_e32 v65, v51, v68
	v_pk_mul_f32 v[50:51], v[58:59], v[68:69] op_sel_hi:[1,0]
	v_mul_f32_e32 v58, v52, v68
	v_mul_f32_e32 v59, v53, v68
	v_pk_mul_f32 v[52:53], v[60:61], v[68:69] op_sel_hi:[1,0]
	v_mul_f32_e32 v60, 0xbfb8aa3b, v67
	v_mul_f32_e32 v61, 0xbfb8aa3b, v69
	v_mul_f32_e32 v62, 0xbfb8aa3b, v62
	v_mul_f32_e32 v63, 0xbfb8aa3b, v63
	v_mul_f32_e32 v64, 0xbfb8aa3b, v64
	v_mul_f32_e32 v65, 0xbfb8aa3b, v65
	v_mul_f32_e32 v58, 0xbfb8aa3b, v58
	v_mul_f32_e32 v59, 0xbfb8aa3b, v59
	v_exp_f32_e32 v60, v60
	v_exp_f32_e32 v61, v61
	v_exp_f32_e32 v62, v62
	v_exp_f32_e32 v63, v63
	v_exp_f32_e32 v64, v64
	v_exp_f32_e32 v65, v65
	v_exp_f32_e32 v58, v58
	v_exp_f32_e32 v59, v59
	v_add_f32_e32 v60, 1.0, v60
	v_add_f32_e32 v61, 1.0, v61
	v_add_f32_e32 v62, 1.0, v62
	v_add_f32_e32 v63, 1.0, v63
	v_add_f32_e32 v64, 1.0, v64
	v_add_f32_e32 v65, 1.0, v65
	v_add_f32_e32 v67, 1.0, v58
	v_add_f32_e32 v68, 1.0, v59
	v_rcp_f32_e32 v58, v60
	v_rcp_f32_e32 v59, v61
	v_rcp_f32_e32 v60, v62
	v_rcp_f32_e32 v61, v63
	v_rcp_f32_e32 v62, v64
	v_rcp_f32_e32 v63, v65
	v_rcp_f32_e32 v64, v67
	v_rcp_f32_e32 v65, v68
	v_pk_mul_f32 v[54:55], v[54:55], v[58:59]
	v_pk_mul_f32 v[56:57], v[56:57], v[60:61]
	v_cvt_pk_bf16_f32 v58, v54, v55
	v_pk_mul_f32 v[50:51], v[50:51], v[62:63]
	v_cvt_pk_bf16_f32 v59, v56, v57
	v_pk_mul_f32 v[52:53], v[52:53], v[64:65]
	v_cvt_pk_bf16_f32 v60, v50, v51
	s_nop 0
	v_cvt_pk_bf16_f32 v61, v52, v53
	global_store_dwordx4 v[70:71], v[58:61], off
	s_nop 1
	v_mov_b64_e32 v[58:59], 0
	s_cbranch_vccnz .LBB0_935
	v_add_u32_e32 v58, 0xffffc080, v180
	v_ashrrev_i32_e32 v58, 2, v58
	v_mad_u64_u32 v[58:59], s[2:3], v58, 30, v[172:173]
	v_ashrrev_i32_e32 v59, 31, v58
	v_lshlrev_b64 v[58:59], 11, v[58:59]
	v_lshl_add_u64 v[58:59], s[20:21], 0, v[58:59]
	v_lshl_add_u64 v[58:59], v[130:131], 2, v[58:59]

; __device__ __forceinline__ unsigned cvt_pk_bf16(float lo, float hi) { unsigned r; asm volatile("v_cvt_pk_bf16_f32 %0, %1, %2" : "=v"(r) : "v"(lo), "v"(hi)); return r; }
; __device__ __forceinline__ float sigmoid_f(float x) { return __builtin_amdgcn_rcpf(1.f + __builtin_amdgcn_exp2f(-1.4426950408889634f * x)); }
;     __device__ __forceinline__ void operator()(const f32x4 (&acc)[2][2][4][2], const Unit& u, int wr, int wc, int fr, int fq) const {
;     ...
;                     const int row = row0 + ai * HALF + m * 16; const float r = __builtin_amdgcn_rsqf(rss[row] * (1.f / 1024.f) + NEPS);
;                     float o[8];
; #pragma unroll
;                     for (int n = 0; n < 2; ++n)
; #pragma unroll
;                         for (int e = 0; e < 4; ++e) o[4 * n + e] = (acc[ai][0][m][n][e] * r) * sigmoid_f(acc[ai][1][m][n][e] * r);
;                     u32x4 w; w.x = cvt_pk_bf16(o[0], o[1]); w.y = cvt_pk_bf16(o[2], o[3]); w.z = cvt_pk_bf16(o[4], o[5]); w.w = cvt_pk_bf16(o[6], o[7]);
;                     *(u32x4*)(U + (size_t)row * 512 + col0) = w;
;                     float* cp = nullptr;
;                     if (!samp) { const int t = row & 4095, b = row >> 12; if (t >= 4066) cp = out + 22806528 + ((size_t)(b * 30 + (t - 4066))) * 512 + col0; }
;                     else { const int sr = row - 16384; cp = out + 199028736 + ((size_t)((sr >> 2) * 30 + 26 + (sr & 3))) * 512 + col0; }
.LBB0_937:
	s_or_b64 exec, exec, s[2:3]
	s_nop 0
	v_readlane_b32 s2, v250, 10
	v_lshlrev_b64 v[50:51], 10, v[180:181]
	v_readlane_b32 s3, v250, 11
	s_waitcnt vmcnt(7)
	v_mov_b32_e32 v52, v241
	v_fmamk_f32 v52, v52, 0x3a800000, v210
	v_rsq_f32_e32 v52, v52
	v_lshl_add_u64 v[50:51], s[2:3], 0, v[50:51]
	v_lshl_add_u64 v[50:51], v[130:131], 1, v[50:51]
	v_add_co_u32_e32 v50, vcc, 0x24000, v50
	v_mul_f32_e32 v53, v38, v52
	v_mul_f32_e32 v54, v39, v52
	v_pk_mul_f32 v[38:39], v[46:47], v[52:53] op_sel_hi:[1,0]
	v_mul_f32_e32 v46, v40, v52
	v_mul_f32_e32 v47, v41, v52
	v_pk_mul_f32 v[40:41], v[48:49], v[52:53] op_sel_hi:[1,0]
	v_mul_f32_e32 v48, v34, v52
	v_mul_f32_e32 v49, v35, v52
	v_pk_mul_f32 v[34:35], v[42:43], v[52:53] op_sel_hi:[1,0]
	v_mul_f32_e32 v42, v36, v52
	v_mul_f32_e32 v43, v37, v52
	v_pk_mul_f32 v[36:37], v[44:45], v[52:53] op_sel_hi:[1,0]
	v_mul_f32_e32 v44, 0xbfb8aa3b, v53
	v_mul_f32_e32 v45, 0xbfb8aa3b, v54
	v_mul_f32_e32 v46, 0xbfb8aa3b, v46
	v_mul_f32_e32 v47, 0xbfb8aa3b, v47
	v_mul_f32_e32 v48, 0xbfb8aa3b, v48
	v_mul_f32_e32 v49, 0xbfb8aa3b, v49
	v_mul_f32_e32 v42, 0xbfb8aa3b, v42
	v_mul_f32_e32 v43, 0xbfb8aa3b, v43
	v_exp_f32_e32 v44, v44
	v_exp_f32_e32 v45, v45
	v_exp_f32_e32 v46, v46
	v_exp_f32_e32 v47, v47
	v_exp_f32_e32 v48, v48
	v_exp_f32_e32 v49, v49
	v_exp_f32_e32 v42, v42
	v_exp_f32_e32 v43, v43
	v_add_f32_e32 v44, 1.0, v44
	v_add_f32_e32 v45, 1.0, v45
	v_add_f32_e32 v46, 1.0, v46
	v_add_f32_e32 v47, 1.0, v47
	v_add_f32_e32 v48, 1.0, v48
	v_add_f32_e32 v49, 1.0, v49
	v_add_f32_e32 v52, 1.0, v42
	v_add_f32_e32 v53, 1.0, v43
	v_rcp_f32_e32 v42, v44
	v_rcp_f32_e32 v43, v45
	v_rcp_f32_e32 v44, v46
	v_rcp_f32_e32 v45, v47
	v_rcp_f32_e32 v46, v48
	v_rcp_f32_e32 v47, v49
	v_rcp_f32_e32 v48, v52
	v_rcp_f32_e32 v49, v53
	v_addc_co_u32_e32 v51, vcc, 0, v51, vcc
	v_pk_mul_f32 v[38:39], v[38:39], v[42:43]
	v_pk_mul_f32 v[40:41], v[40:41], v[44:45]
	v_cvt_pk_bf16_f32 v42, v38, v39
	s_and_b64 vcc, exec, s[10:11]
	v_cvt_pk_bf16_f32 v43, v40, v41
	v_pk_mul_f32 v[34:35], v[34:35], v[46:47]
	v_pk_mul_f32 v[36:37], v[36:37], v[48:49]
	v_cvt_pk_bf16_f32 v44, v34, v35
	s_nop 0
	v_cvt_pk_bf16_f32 v45, v36, v37
	global_store_dwordx4 v[50:51], v[42:45], off
	s_nop 1
	v_mov_b64_e32 v[42:43], 0
	s_cbranch_vccnz .LBB0_939
	v_add_u32_e32 v42, 0xffffc090, v180
	v_ashrrev_i32_e32 v42, 2, v42
	v_mad_u64_u32 v[42:43], s[2:3], v42, 30, v[172:173]
	v_ashrrev_i32_e32 v43, 31, v42
	v_lshlrev_b64 v[42:43], 11, v[42:43]
	v_lshl_add_u64 v[42:43], s[20:21], 0, v[42:43]
	v_lshl_add_u64 v[42:43], v[130:131], 2, v[42:43]

; __device__ __forceinline__ unsigned cvt_pk_bf16(float lo, float hi) { unsigned r; asm volatile("v_cvt_pk_bf16_f32 %0, %1, %2" : "=v"(r) : "v"(lo), "v"(hi)); return r; }
; __device__ __forceinline__ float sigmoid_f(float x) { return __builtin_amdgcn_rcpf(1.f + __builtin_amdgcn_exp2f(-1.4426950408889634f * x)); }
;     __device__ __forceinline__ void operator()(const f32x4 (&acc)[2][2][4][2], const Unit& u, int wr, int wc, int fr, int fq) const {
;     ...
;                     const int row = row0 + ai * HALF + m * 16; const float r = __builtin_amdgcn_rsqf(rss[row] * (1.f / 1024.f) + NEPS);
;                     float o[8];
; #pragma unroll
;                     for (int n = 0; n < 2; ++n)
; #pragma unroll
;                         for (int e = 0; e < 4; ++e) o[4 * n + e] = (acc[ai][0][m][n][e] * r) * sigmoid_f(acc[ai][1][m][n][e] * r);
;                     u32x4 w; w.x = cvt_pk_bf16(o[0], o[1]); w.y = cvt_pk_bf16(o[2], o[3]); w.z = cvt_pk_bf16(o[4], o[5]); w.w = cvt_pk_bf16(o[6], o[7]);
;                     *(u32x4*)(U + (size_t)row * 512 + col0) = w;
;                     float* cp = nullptr;
;                     if (!samp) { const int t = row & 4095, b = row >> 12; if (t >= 4066) cp = out + 22806528 + ((size_t)(b * 30 + (t - 4066))) * 512 + col0; }
;                     else { const int sr = row - 16384; cp = out + 199028736 + ((size_t)((sr >> 2) * 30 + 26 + (sr & 3))) * 512 + col0; }
.LBB0_941:
	s_or_b64 exec, exec, s[2:3]
	s_nop 0
	v_ashrrev_i32_e32 v35, 12, v66
	v_add_u32_e32 v34, 0xa0, v180
	v_mad_i32_i24 v36, v35, 30, v212
	v_ashrrev_i32_e32 v35, 31, v34
	v_lshlrev_b64 v[40:41], 10, v[34:35]
	v_readlane_b32 s2, v250, 10
	v_readlane_b32 s3, v250, 11
	s_and_b64 vcc, exec, s[8:9]
	s_waitcnt vmcnt(7)
	v_mov_b32_e32 v37, v242
	v_fmamk_f32 v37, v37, 0x3a800000, v210
	v_rsq_f32_e32 v38, v37
	v_lshl_add_u64 v[40:41], s[2:3], 0, v[40:41]
	v_lshl_add_u64 v[40:41], v[130:131], 1, v[40:41]
	s_mov_b64 s[2:3], -1
	v_mul_f32_e32 v35, v22, v38
	v_mul_f32_e32 v37, v23, v38
	v_pk_mul_f32 v[22:23], v[30:31], v[38:39] op_sel_hi:[1,0]
	v_mul_f32_e32 v30, v24, v38
	v_mul_f32_e32 v31, v25, v38
	v_pk_mul_f32 v[24:25], v[32:33], v[38:39] op_sel_hi:[1,0]
	v_mul_f32_e32 v32, v18, v38
	v_mul_f32_e32 v33, v19, v38
	v_pk_mul_f32 v[18:19], v[26:27], v[38:39] op_sel_hi:[1,0]
	v_mul_f32_e32 v26, v20, v38
	v_mul_f32_e32 v27, v21, v38
	v_pk_mul_f32 v[20:21], v[28:29], v[38:39] op_sel_hi:[1,0]
	v_mul_f32_e32 v28, 0xbfb8aa3b, v35
	v_mul_f32_e32 v29, 0xbfb8aa3b, v37
	v_mul_f32_e32 v30, 0xbfb8aa3b, v30
	v_mul_f32_e32 v31, 0xbfb8aa3b, v31
	v_mul_f32_e32 v32, 0xbfb8aa3b, v32
	v_mul_f32_e32 v33, 0xbfb8aa3b, v33
	v_mul_f32_e32 v26, 0xbfb8aa3b, v26
	v_mul_f32_e32 v27, 0xbfb8aa3b, v27
	v_exp_f32_e32 v28, v28
	v_exp_f32_e32 v29, v29
	v_exp_f32_e32 v30, v30
	v_exp_f32_e32 v31, v31
	v_exp_f32_e32 v32, v32
	v_exp_f32_e32 v33, v33
	v_exp_f32_e32 v26, v26
	v_exp_f32_e32 v27, v27
	v_add_f32_e32 v28, 1.0, v28
	v_add_f32_e32 v29, 1.0, v29
	v_add_f32_e32 v30, 1.0, v30
	v_add_f32_e32 v31, 1.0, v31
	v_add_f32_e32 v32, 1.0, v32
	v_add_f32_e32 v33, 1.0, v33
	v_add_f32_e32 v35, 1.0, v26
	v_add_f32_e32 v37, 1.0, v27
	v_rcp_f32_e32 v26, v28
	v_rcp_f32_e32 v27, v29
	v_rcp_f32_e32 v28, v30
	v_rcp_f32_e32 v29, v31
	v_rcp_f32_e32 v30, v32
	v_rcp_f32_e32 v31, v33
	v_rcp_f32_e32 v32, v35
	v_rcp_f32_e32 v33, v37
	v_pk_mul_f32 v[22:23], v[22:23], v[26:27]
	v_pk_mul_f32 v[24:25], v[24:25], v[28:29]
	v_pk_mul_f32 v[18:19], v[18:19], v[30:31]
	v_pk_mul_f32 v[20:21], v[20:21], v[32:33]
	v_cvt_pk_bf16_f32 v26, v22, v23
	v_cvt_pk_bf16_f32 v27, v24, v25
	v_cvt_pk_bf16_f32 v28, v18, v19
	s_nop 0
	v_cvt_pk_bf16_f32 v29, v20, v21
	global_store_dwordx4 v[40:41], v[26:29], off
	s_cbranch_vccnz .LBB0_956
	s_nop 0
	v_and_b32_e32 v28, 0xfef, v34
	v_add_u32_e32 v26, v36, v28
	v_ashrrev_i32_e32 v27, 31, v26
	v_lshlrev_b64 v[26:27], 11, v[26:27]
	v_lshl_add_u64 v[26:27], s[22:23], 0, v[26:27]
	v_lshl_add_u64 v[26:27], v[130:131], 2, v[26:27]
	v_cmp_lt_u32_e32 vcc, s78, v28
	s_nop 1
	v_cndmask_b32_e32 v27, 0, v27, vcc
	v_cndmask_b32_e32 v26, 0, v26, vcc
	s_cbranch_execz .LBB0_957

; __device__ __forceinline__ unsigned cvt_pk_bf16(float lo, float hi) { unsigned r; asm volatile("v_cvt_pk_bf16_f32 %0, %1, %2" : "=v"(r) : "v"(lo), "v"(hi)); return r; }
; __device__ __forceinline__ float sigmoid_f(float x) { return __builtin_amdgcn_rcpf(1.f + __builtin_amdgcn_exp2f(-1.4426950408889634f * x)); }
;     __device__ __forceinline__ void operator()(const f32x4 (&acc)[2][2][4][2], const Unit& u, int wr, int wc, int fr, int fq) const {
;     ...
;                     const int row = row0 + ai * HALF + m * 16; const float r = __builtin_amdgcn_rsqf(rss[row] * (1.f / 1024.f) + NEPS);
;                     float o[8];
; #pragma unroll
;                     for (int n = 0; n < 2; ++n)
; #pragma unroll
;                         for (int e = 0; e < 4; ++e) o[4 * n + e] = (acc[ai][0][m][n][e] * r) * sigmoid_f(acc[ai][1][m][n][e] * r);
;                     u32x4 w; w.x = cvt_pk_bf16(o[0], o[1]); w.y = cvt_pk_bf16(o[2], o[3]); w.z = cvt_pk_bf16(o[4], o[5]); w.w = cvt_pk_bf16(o[6], o[7]);
;                     *(u32x4*)(U + (size_t)row * 512 + col0) = w;
;                     float* cp = nullptr;
;                     if (!samp) { const int t = row & 4095, b = row >> 12; if (t >= 4066) cp = out + 22806528 + ((size_t)(b * 30 + (t - 4066))) * 512 + col0; }
;                     else { const int sr = row - 16384; cp = out + 199028736 + ((size_t)((sr >> 2) * 30 + 26 + (sr & 3))) * 512 + col0; }
.LBB0_945:
	s_or_b64 exec, exec, s[2:3]
	s_nop 0
	v_add_u32_e32 v18, 0xb0, v180
	v_ashrrev_i32_e32 v19, 31, v18
	v_lshlrev_b64 v[22:23], 10, v[18:19]
	v_readlane_b32 s2, v250, 10
	v_readlane_b32 s3, v250, 11
	s_and_b64 vcc, exec, s[8:9]
	s_waitcnt vmcnt(7)
	v_mov_b32_e32 v20, v243
	v_fmamk_f32 v20, v20, 0x3a800000, v210
	v_rsq_f32_e32 v20, v20
	v_lshl_add_u64 v[22:23], s[2:3], 0, v[22:23]
	v_lshl_add_u64 v[22:23], v[130:131], 1, v[22:23]
	s_mov_b64 s[2:3], -1
	v_mul_f32_e32 v21, v7, v20
	v_mul_f32_e32 v19, v6, v20
	v_pk_mul_f32 v[6:7], v[14:15], v[20:21] op_sel_hi:[1,0]
	v_mul_f32_e32 v14, v8, v20
	v_mul_f32_e32 v15, v9, v20
	v_pk_mul_f32 v[8:9], v[16:17], v[20:21] op_sel_hi:[1,0]
	v_mul_f32_e32 v16, v2, v20
	v_mul_f32_e32 v17, v3, v20
	v_pk_mul_f32 v[2:3], v[10:11], v[20:21] op_sel_hi:[1,0]
	v_mul_f32_e32 v10, v4, v20
	v_mul_f32_e32 v11, v5, v20
	v_pk_mul_f32 v[4:5], v[12:13], v[20:21] op_sel_hi:[1,0]
	v_mul_f32_e32 v12, 0xbfb8aa3b, v19
	v_mul_f32_e32 v13, 0xbfb8aa3b, v21
	v_mul_f32_e32 v14, 0xbfb8aa3b, v14
	v_mul_f32_e32 v15, 0xbfb8aa3b, v15
	v_mul_f32_e32 v16, 0xbfb8aa3b, v16
	v_mul_f32_e32 v17, 0xbfb8aa3b, v17
	v_mul_f32_e32 v10, 0xbfb8aa3b, v10
	v_mul_f32_e32 v11, 0xbfb8aa3b, v11
	v_exp_f32_e32 v12, v12
	v_exp_f32_e32 v13, v13
	v_exp_f32_e32 v14, v14
	v_exp_f32_e32 v15, v15
	v_exp_f32_e32 v16, v16
	v_exp_f32_e32 v17, v17
	v_exp_f32_e32 v10, v10
	v_exp_f32_e32 v11, v11
	v_add_f32_e32 v12, 1.0, v12
	v_add_f32_e32 v13, 1.0, v13
	v_add_f32_e32 v14, 1.0, v14
	v_add_f32_e32 v15, 1.0, v15
	v_add_f32_e32 v16, 1.0, v16
	v_add_f32_e32 v17, 1.0, v17
	v_add_f32_e32 v19, 1.0, v10
	v_add_f32_e32 v20, 1.0, v11
	v_rcp_f32_e32 v10, v12
	v_rcp_f32_e32 v11, v13
	v_rcp_f32_e32 v12, v14
	v_rcp_f32_e32 v13, v15
	v_rcp_f32_e32 v14, v16
	v_rcp_f32_e32 v15, v17
	v_rcp_f32_e32 v16, v19
	v_rcp_f32_e32 v17, v20
	v_pk_mul_f32 v[6:7], v[6:7], v[10:11]
	v_pk_mul_f32 v[8:9], v[8:9], v[12:13]
	v_pk_mul_f32 v[2:3], v[2:3], v[14:15]
	v_pk_mul_f32 v[4:5], v[4:5], v[16:17]
	v_cvt_pk_bf16_f32 v10, v6, v7
	v_cvt_pk_bf16_f32 v11, v8, v9
	v_cvt_pk_bf16_f32 v12, v2, v3
	s_nop 0
	v_cvt_pk_bf16_f32 v13, v4, v5
	global_store_dwordx4 v[22:23], v[10:13], off
	s_cbranch_vccnz .LBB0_958
	s_nop 0
	v_and_b32_e32 v12, 0xfff, v18
	v_add_u32_e32 v10, v36, v12
	v_ashrrev_i32_e32 v11, 31, v10
	v_lshlrev_b64 v[10:11], 11, v[10:11]
	v_lshl_add_u64 v[10:11], s[22:23], 0, v[10:11]
	v_lshl_add_u64 v[10:11], v[130:131], 2, v[10:11]
	v_cmp_lt_u32_e32 vcc, s78, v12
	s_nop 1
	v_cndmask_b32_e32 v11, 0, v11, vcc
	v_cndmask_b32_e32 v10, 0, v10, vcc
	s_cbranch_execz .LBB0_959
